# phase 1: non-temporal hint on the streaming x row loads
# speedup vs baseline: 1.0045x; 1.0024x over previous
.Lp1_nob0:
	s_lshl_b32 s8, s6, 12
	s_add_u32 s8, s40, s8
	s_addc_u32 s9, s41, 0
	global_load_dwordx4 v[68:71], v0, s[8:9] nt
	global_load_dwordx4 v[72:75], v0, s[8:9] offset:1024 nt
	global_load_dwordx4 v[76:79], v0, s[8:9] offset:2048 nt
	global_load_dwordx4 v[80:83], v0, s[8:9] offset:3072 nt
	s_add_u32 s8, s8, 0x800000
	s_addc_u32 s9, s9, 0
	global_load_dwordx4 v[84:87], v0, s[8:9] nt
	global_load_dwordx4 v[88:91], v0, s[8:9] offset:1024 nt
	global_load_dwordx4 v[92:95], v0, s[8:9] offset:2048 nt
	global_load_dwordx4 v[96:99], v0, s[8:9] offset:3072 nt
	s_add_u32 s8, s8, 0x800000
	s_addc_u32 s9, s9, 0
	global_load_dwordx4 v[100:103], v0, s[8:9] nt
	global_load_dwordx4 v[104:107], v0, s[8:9] offset:1024 nt
	global_load_dwordx4 v[108:111], v0, s[8:9] offset:2048 nt
	global_load_dwordx4 v[112:115], v0, s[8:9] offset:3072 nt
	s_add_u32 s8, s8, 0x800000
	s_addc_u32 s9, s9, 0
	global_load_dwordx4 v[116:119], v0, s[8:9] nt
	global_load_dwordx4 v[120:123], v0, s[8:9] offset:1024 nt
	global_load_dwordx4 v[124:127], v0, s[8:9] offset:2048 nt
	global_load_dwordx4 v[128:131], v0, s[8:9] offset:3072 nt
	s_add_u32 s8, s8, 0x800000
	s_addc_u32 s9, s9, 0
	s_lshl_b32 s10, s6, 11
	s_add_u32 s10, s10, 0x1e85000
	s_addc_u32 s11, 0, 0
	s_add_u32 s10, s74, s10
	s_addc_u32 s11, s75, s11
	s_cmpk_lt_u32 s16, 0xb0
	s_cbranch_scc0 .Lp1_nob1
	s_waitcnt vmcnt(16)
	v_readlane_b32 s24, v189, 0
	v_readlane_b32 s25, v189, 16
	v_readlane_b32 s26, v189, 32
	v_readlane_b32 s27, v189, 48
	v_mul_f32_e32 v216, s24, v148
	v_mul_f32_e32 v217, s24, v149
	v_mul_f32_e32 v218, s24, v150
	v_mul_f32_e32 v219, s24, v151
	v_mul_f32_e32 v220, s25, v148
	v_mul_f32_e32 v221, s25, v149
	v_mul_f32_e32 v222, s25, v150
	v_mul_f32_e32 v223, s25, v151
	v_mul_f32_e32 v224, s26, v148
	v_mul_f32_e32 v225, s26, v149
	v_mul_f32_e32 v226, s26, v150
	v_mul_f32_e32 v227, s26, v151
	v_mul_f32_e32 v228, s27, v148
	v_mul_f32_e32 v229, s27, v149
	v_mul_f32_e32 v230, s27, v150
	v_mul_f32_e32 v231, s27, v151
	v_readlane_b32 s24, v189, 1
	v_readlane_b32 s25, v189, 17
	v_readlane_b32 s26, v189, 33
	v_readlane_b32 s27, v189, 49
	v_fmac_f32_e32 v216, s24, v152
	v_fmac_f32_e32 v217, s24, v153
	v_fmac_f32_e32 v218, s24, v154
	v_fmac_f32_e32 v219, s24, v155
	v_fmac_f32_e32 v220, s25, v152
	v_fmac_f32_e32 v221, s25, v153
	v_fmac_f32_e32 v222, s25, v154
	v_fmac_f32_e32 v223, s25, v155
	v_fmac_f32_e32 v224, s26, v152
	v_fmac_f32_e32 v225, s26, v153
	v_fmac_f32_e32 v226, s26, v154
	v_fmac_f32_e32 v227, s26, v155
	v_fmac_f32_e32 v228, s27, v152
	v_fmac_f32_e32 v229, s27, v153
	v_fmac_f32_e32 v230, s27, v154
	v_fmac_f32_e32 v231, s27, v155
	v_readlane_b32 s24, v189, 2
	v_readlane_b32 s25, v189, 18
	v_readlane_b32 s26, v189, 34
	v_readlane_b32 s27, v189, 50
	v_fmac_f32_e32 v216, s24, v156
	v_fmac_f32_e32 v217, s24, v157
	v_fmac_f32_e32 v218, s24, v158
	v_fmac_f32_e32 v219, s24, v159
	v_fmac_f32_e32 v220, s25, v156
	v_fmac_f32_e32 v221, s25, v157
	v_fmac_f32_e32 v222, s25, v158
	v_fmac_f32_e32 v223, s25, v159
	v_fmac_f32_e32 v224, s26, v156
	v_fmac_f32_e32 v225, s26, v157
	v_fmac_f32_e32 v226, s26, v158
	v_fmac_f32_e32 v227, s26, v159
	v_fmac_f32_e32 v228, s27, v156
	v_fmac_f32_e32 v229, s27, v157
	v_fmac_f32_e32 v230, s27, v158
	v_fmac_f32_e32 v231, s27, v159
	v_readlane_b32 s24, v189, 3
	v_readlane_b32 s25, v189, 19
	v_readlane_b32 s26, v189, 35
	v_readlane_b32 s27, v189, 51
	v_fmac_f32_e32 v216, s24, v160
	v_fmac_f32_e32 v217, s24, v161
	v_fmac_f32_e32 v218, s24, v162
	v_fmac_f32_e32 v219, s24, v163
	v_fmac_f32_e32 v220, s25, v160
	v_fmac_f32_e32 v221, s25, v161
	v_fmac_f32_e32 v222, s25, v162
	v_fmac_f32_e32 v223, s25, v163
	v_fmac_f32_e32 v224, s26, v160
	v_fmac_f32_e32 v225, s26, v161
	v_fmac_f32_e32 v226, s26, v162
	v_fmac_f32_e32 v227, s26, v163
	v_fmac_f32_e32 v228, s27, v160
	v_fmac_f32_e32 v229, s27, v161
	v_fmac_f32_e32 v230, s27, v162
	v_fmac_f32_e32 v231, s27, v163
	v_readlane_b32 s24, v189, 4
	v_readlane_b32 s25, v189, 20
	v_readlane_b32 s26, v189, 36
	v_readlane_b32 s27, v189, 52
	v_fmac_f32_e32 v216, s24, v164
	v_fmac_f32_e32 v217, s24, v165
	v_fmac_f32_e32 v218, s24, v166
	v_fmac_f32_e32 v219, s24, v167
	v_fmac_f32_e32 v220, s25, v164
	v_fmac_f32_e32 v221, s25, v165
	v_fmac_f32_e32 v222, s25, v166
	v_fmac_f32_e32 v223, s25, v167
	v_fmac_f32_e32 v224, s26, v164
	v_fmac_f32_e32 v225, s26, v165
	v_fmac_f32_e32 v226, s26, v166
	v_fmac_f32_e32 v227, s26, v167
	v_fmac_f32_e32 v228, s27, v164
	v_fmac_f32_e32 v229, s27, v165
	v_fmac_f32_e32 v230, s27, v166
	v_fmac_f32_e32 v231, s27, v167
	v_readlane_b32 s24, v189, 5
	v_readlane_b32 s25, v189, 21
	v_readlane_b32 s26, v189, 37
	v_readlane_b32 s27, v189, 53
	v_fmac_f32_e32 v216, s24, v168
	v_fmac_f32_e32 v217, s24, v169
	v_fmac_f32_e32 v218, s24, v170
	v_fmac_f32_e32 v219, s24, v171
	v_fmac_f32_e32 v220, s25, v168
	v_fmac_f32_e32 v221, s25, v169
	v_fmac_f32_e32 v222, s25, v170
	v_fmac_f32_e32 v223, s25, v171
	v_fmac_f32_e32 v224, s26, v168
	v_fmac_f32_e32 v225, s26, v169
	v_fmac_f32_e32 v226, s26, v170
	v_fmac_f32_e32 v227, s26, v171
	v_fmac_f32_e32 v228, s27, v168
	v_fmac_f32_e32 v229, s27, v169
	v_fmac_f32_e32 v230, s27, v170
	v_fmac_f32_e32 v231, s27, v171
	v_readlane_b32 s24, v189, 6
	v_readlane_b32 s25, v189, 22
	v_readlane_b32 s26, v189, 38
	v_readlane_b32 s27, v189, 54
	v_fmac_f32_e32 v216, s24, v172
	v_fmac_f32_e32 v217, s24, v173
	v_fmac_f32_e32 v218, s24, v174
	v_fmac_f32_e32 v219, s24, v175
	v_fmac_f32_e32 v220, s25, v172
	v_fmac_f32_e32 v221, s25, v173
	v_fmac_f32_e32 v222, s25, v174
	v_fmac_f32_e32 v223, s25, v175
	v_fmac_f32_e32 v224, s26, v172
	v_fmac_f32_e32 v225, s26, v173
	v_fmac_f32_e32 v226, s26, v174
	v_fmac_f32_e32 v227, s26, v175
	v_fmac_f32_e32 v228, s27, v172
	v_fmac_f32_e32 v229, s27, v173
	v_fmac_f32_e32 v230, s27, v174
	v_fmac_f32_e32 v231, s27, v175
	v_readlane_b32 s24, v189, 7
	v_readlane_b32 s25, v189, 23
	v_readlane_b32 s26, v189, 39
	v_readlane_b32 s27, v189, 55
	v_fmac_f32_e32 v216, s24, v176
	v_fmac_f32_e32 v217, s24, v177
	v_fmac_f32_e32 v218, s24, v178
	v_fmac_f32_e32 v219, s24, v179
	v_fmac_f32_e32 v220, s25, v176
	v_fmac_f32_e32 v221, s25, v177
	v_fmac_f32_e32 v222, s25, v178
	v_fmac_f32_e32 v223, s25, v179
	v_fmac_f32_e32 v224, s26, v176
	v_fmac_f32_e32 v225, s26, v177
	v_fmac_f32_e32 v226, s26, v178
	v_fmac_f32_e32 v227, s26, v179
	v_fmac_f32_e32 v228, s27, v176
	v_fmac_f32_e32 v229, s27, v177
	v_fmac_f32_e32 v230, s27, v178
	v_fmac_f32_e32 v231, s27, v179
	v_readlane_b32 s24, v189, 8
	v_readlane_b32 s25, v189, 24
	v_readlane_b32 s26, v189, 40
	v_readlane_b32 s27, v189, 56
	v_fmac_f32_e32 v216, s24, v180
	v_fmac_f32_e32 v217, s24, v181
	v_fmac_f32_e32 v218, s24, v182
	v_fmac_f32_e32 v219, s24, v183
	v_fmac_f32_e32 v220, s25, v180
	v_fmac_f32_e32 v221, s25, v181
	v_fmac_f32_e32 v222, s25, v182
	v_fmac_f32_e32 v223, s25, v183
	v_fmac_f32_e32 v224, s26, v180
	v_fmac_f32_e32 v225, s26, v181
	v_fmac_f32_e32 v226, s26, v182
	v_fmac_f32_e32 v227, s26, v183
	v_fmac_f32_e32 v228, s27, v180
	v_fmac_f32_e32 v229, s27, v181
	v_fmac_f32_e32 v230, s27, v182
	v_fmac_f32_e32 v231, s27, v183
	v_readlane_b32 s24, v189, 9
	v_readlane_b32 s25, v189, 25
	v_readlane_b32 s26, v189, 41
	v_readlane_b32 s27, v189, 57
	v_fmac_f32_e32 v216, s24, v184
	v_fmac_f32_e32 v217, s24, v185
	v_fmac_f32_e32 v218, s24, v186
	v_fmac_f32_e32 v219, s24, v187
	v_fmac_f32_e32 v220, s25, v184
	v_fmac_f32_e32 v221, s25, v185
	v_fmac_f32_e32 v222, s25, v186
	v_fmac_f32_e32 v223, s25, v187
	v_fmac_f32_e32 v224, s26, v184
	v_fmac_f32_e32 v225, s26, v185
	v_fmac_f32_e32 v226, s26, v186
	v_fmac_f32_e32 v227, s26, v187
	v_fmac_f32_e32 v228, s27, v184
	v_fmac_f32_e32 v229, s27, v185
	v_fmac_f32_e32 v230, s27, v186
	v_fmac_f32_e32 v231, s27, v187
	v_readlane_b32 s24, v189, 10
	v_readlane_b32 s25, v189, 26
	v_readlane_b32 s26, v189, 42
	v_readlane_b32 s27, v189, 58
	v_fmac_f32_e32 v216, s24, v192
	v_fmac_f32_e32 v217, s24, v193
	v_fmac_f32_e32 v218, s24, v194
	v_fmac_f32_e32 v219, s24, v195
	v_fmac_f32_e32 v220, s25, v192
	v_fmac_f32_e32 v221, s25, v193
	v_fmac_f32_e32 v222, s25, v194
	v_fmac_f32_e32 v223, s25, v195
	v_fmac_f32_e32 v224, s26, v192
	v_fmac_f32_e32 v225, s26, v193
	v_fmac_f32_e32 v226, s26, v194
	v_fmac_f32_e32 v227, s26, v195
	v_fmac_f32_e32 v228, s27, v192
	v_fmac_f32_e32 v229, s27, v193
	v_fmac_f32_e32 v230, s27, v194
	v_fmac_f32_e32 v231, s27, v195
	v_readlane_b32 s24, v189, 11
	v_readlane_b32 s25, v189, 27
	v_readlane_b32 s26, v189, 43
	v_readlane_b32 s27, v189, 59
	v_fmac_f32_e32 v216, s24, v196
	v_fmac_f32_e32 v217, s24, v197
	v_fmac_f32_e32 v218, s24, v198
	v_fmac_f32_e32 v219, s24, v199
	v_fmac_f32_e32 v220, s25, v196
	v_fmac_f32_e32 v221, s25, v197
	v_fmac_f32_e32 v222, s25, v198
	v_fmac_f32_e32 v223, s25, v199
	v_fmac_f32_e32 v224, s26, v196
	v_fmac_f32_e32 v225, s26, v197
	v_fmac_f32_e32 v226, s26, v198
	v_fmac_f32_e32 v227, s26, v199
	v_fmac_f32_e32 v228, s27, v196
	v_fmac_f32_e32 v229, s27, v197
	v_fmac_f32_e32 v230, s27, v198
	v_fmac_f32_e32 v231, s27, v199
	v_readlane_b32 s24, v189, 12
	v_readlane_b32 s25, v189, 28
	v_readlane_b32 s26, v189, 44
	v_readlane_b32 s27, v189, 60
	v_fmac_f32_e32 v216, s24, v200
	v_fmac_f32_e32 v217, s24, v201
	v_fmac_f32_e32 v218, s24, v202
	v_fmac_f32_e32 v219, s24, v203
	v_fmac_f32_e32 v220, s25, v200
	v_fmac_f32_e32 v221, s25, v201
	v_fmac_f32_e32 v222, s25, v202
	v_fmac_f32_e32 v223, s25, v203
	v_fmac_f32_e32 v224, s26, v200
	v_fmac_f32_e32 v225, s26, v201
	v_fmac_f32_e32 v226, s26, v202
	v_fmac_f32_e32 v227, s26, v203
	v_fmac_f32_e32 v228, s27, v200
	v_fmac_f32_e32 v229, s27, v201
	v_fmac_f32_e32 v230, s27, v202
	v_fmac_f32_e32 v231, s27, v203
	v_readlane_b32 s24, v189, 13
	v_readlane_b32 s25, v189, 29
	v_readlane_b32 s26, v189, 45
	v_readlane_b32 s27, v189, 61
	v_fmac_f32_e32 v216, s24, v204
	v_fmac_f32_e32 v217, s24, v205
	v_fmac_f32_e32 v218, s24, v206
	v_fmac_f32_e32 v219, s24, v207
	v_fmac_f32_e32 v220, s25, v204
	v_fmac_f32_e32 v221, s25, v205
	v_fmac_f32_e32 v222, s25, v206
	v_fmac_f32_e32 v223, s25, v207
	v_fmac_f32_e32 v224, s26, v204
	v_fmac_f32_e32 v225, s26, v205
	v_fmac_f32_e32 v226, s26, v206
	v_fmac_f32_e32 v227, s26, v207
	v_fmac_f32_e32 v228, s27, v204
	v_fmac_f32_e32 v229, s27, v205
	v_fmac_f32_e32 v230, s27, v206
	v_fmac_f32_e32 v231, s27, v207
	v_readlane_b32 s24, v189, 14
	v_readlane_b32 s25, v189, 30
	v_readlane_b32 s26, v189, 46
	v_readlane_b32 s27, v189, 62
	v_fmac_f32_e32 v216, s24, v208
	v_fmac_f32_e32 v217, s24, v209
	v_fmac_f32_e32 v218, s24, v210
	v_fmac_f32_e32 v219, s24, v211
	v_fmac_f32_e32 v220, s25, v208
	v_fmac_f32_e32 v221, s25, v209
	v_fmac_f32_e32 v222, s25, v210
	v_fmac_f32_e32 v223, s25, v211
	v_fmac_f32_e32 v224, s26, v208
	v_fmac_f32_e32 v225, s26, v209
	v_fmac_f32_e32 v226, s26, v210
	v_fmac_f32_e32 v227, s26, v211
	v_fmac_f32_e32 v228, s27, v208
	v_fmac_f32_e32 v229, s27, v209
	v_fmac_f32_e32 v230, s27, v210
	v_fmac_f32_e32 v231, s27, v211
	v_readlane_b32 s24, v189, 15
	v_readlane_b32 s25, v189, 31
	v_readlane_b32 s26, v189, 47
	v_readlane_b32 s27, v189, 63
	v_fmac_f32_e32 v216, s24, v212
	v_fmac_f32_e32 v217, s24, v213
	v_fmac_f32_e32 v218, s24, v214
	v_fmac_f32_e32 v219, s24, v215
	v_fmac_f32_e32 v220, s25, v212
	v_fmac_f32_e32 v221, s25, v213
	v_fmac_f32_e32 v222, s25, v214
	v_fmac_f32_e32 v223, s25, v215
	v_fmac_f32_e32 v224, s26, v212
	v_fmac_f32_e32 v225, s26, v213
	v_fmac_f32_e32 v226, s26, v214
	v_fmac_f32_e32 v227, s26, v215
	v_fmac_f32_e32 v228, s27, v212
	v_fmac_f32_e32 v229, s27, v213
	v_fmac_f32_e32 v230, s27, v214
	v_fmac_f32_e32 v231, s27, v215
	s_lshl_b32 s19, s7, 12
	v_add_u32_e32 v248, s19, v0
	ds_write_b128 v248, v[216:219]
	ds_write_b128 v248, v[220:223] offset:1024
	ds_write_b128 v248, v[224:227] offset:2048
	ds_write_b128 v248, v[228:231] offset:3072
	s_waitcnt lgkmcnt(0)
	s_barrier
	s_lshl_b32 s19, s7, 9
	v_add_u32_e32 v248, s19, v1
	ds_read_b64 v[216:217], v248
	ds_read_b64 v[218:219], v248 offset:4096
	ds_read_b64 v[220:221], v248 offset:8192
	ds_read_b64 v[222:223], v248 offset:12288
	ds_read_b64 v[224:225], v248 offset:16384
	ds_read_b64 v[226:227], v248 offset:20480
	ds_read_b64 v[228:229], v248 offset:24576
	ds_read_b64 v[230:231], v248 offset:28672
	s_waitcnt lgkmcnt(0)
	v_pk_add_f32 v[216:217], v[216:217], v[218:219]
	v_pk_add_f32 v[216:217], v[216:217], v[220:221]
	v_pk_add_f32 v[216:217], v[216:217], v[222:223]
	v_pk_add_f32 v[216:217], v[216:217], v[224:225]
	v_pk_add_f32 v[216:217], v[216:217], v[226:227]
	v_pk_add_f32 v[216:217], v[216:217], v[228:229]
	v_pk_add_f32 v[216:217], v[216:217], v[230:231]
	s_and_b32 s19, s7, 1
	s_lshl_b32 s19, s19, 9
	s_lshl_b32 s24, s18, 10
	s_add_i32 s19, s19, s24
	v_add_u32_e32 v248, s19, v1
	s_lshr_b32 s24, s7, 1
	s_mul_i32 s24, s24, 0x5800
	s_add_u32 s14, s74, 0x47000
	s_addc_u32 s15, s75, 0
	s_add_u32 s14, s14, s24
	s_addc_u32 s15, s15, 0
	global_atomic_add_f32 v248, v216, s[14:15]
	global_atomic_add_f32 v248, v217, s[14:15] offset:4
.Lp1_nob1:
	s_waitcnt vmcnt(12)
	v_pk_add_f32 v[52:53], v[52:53], v[18:19]
	v_pk_add_f32 v[54:55], v[54:55], v[18:19]
	v_pk_add_f32 v[56:57], v[56:57], v[18:19]
	v_pk_add_f32 v[58:59], v[58:59], v[18:19]
	v_pk_add_f32 v[60:61], v[60:61], v[18:19]
	v_pk_add_f32 v[62:63], v[62:63], v[18:19]
	v_pk_add_f32 v[64:65], v[64:65], v[18:19]
	v_pk_add_f32 v[66:67], v[66:67], v[18:19]
	s_add_u32 s14, s12, 0x6000
	s_addc_u32 s15, s13, 0
	s_add_u32 s16, s14, 0x1000
	s_addc_u32 s17, s15, 0
	global_load_dwordx4 v[148:151], v0, s[14:15]
	global_load_dwordx4 v[152:155], v0, s[14:15] offset:1024
	global_load_dwordx4 v[156:159], v0, s[14:15] offset:2048
	global_load_dwordx4 v[160:163], v0, s[14:15] offset:3072
	global_load_dwordx4 v[164:167], v0, s[16:17]
	global_load_dwordx4 v[168:171], v0, s[16:17] offset:1024
	global_load_dwordx4 v[172:175], v0, s[16:17] offset:2048
	global_load_dwordx4 v[176:179], v0, s[16:17] offset:3072
	v_pk_mul_f32 v[4:5], v[68:69], v[68:69]
	v_pk_fma_f32 v[4:5], v[70:71], v[70:71], v[4:5]
	v_pk_fma_f32 v[4:5], v[72:73], v[72:73], v[4:5]
	v_pk_fma_f32 v[4:5], v[74:75], v[74:75], v[4:5]
	v_pk_fma_f32 v[4:5], v[76:77], v[76:77], v[4:5]
	v_pk_fma_f32 v[4:5], v[78:79], v[78:79], v[4:5]
	v_pk_fma_f32 v[4:5], v[80:81], v[80:81], v[4:5]
	v_pk_fma_f32 v[4:5], v[82:83], v[82:83], v[4:5]
	v_add_f32_e32 v4, v4, v5
	s_nop 1
	v_add_f32_dpp v4, v4, v4 quad_perm:[1,0,3,2] row_mask:0xf bank_mask:0xf
	s_nop 1
	v_add_f32_dpp v4, v4, v4 quad_perm:[2,3,0,1] row_mask:0xf bank_mask:0xf
	s_nop 1
	v_add_f32_dpp v4, v4, v4 row_half_mirror row_mask:0xf bank_mask:0xf
	s_nop 1
	v_add_f32_dpp v4, v4, v4 row_mirror row_mask:0xf bank_mask:0xf
	s_nop 1
	v_add_f32_dpp v4, v4, v4 row_bcast:15 row_mask:0xa bank_mask:0xf
	s_nop 1
	v_add_f32_dpp v4, v4, v4 row_bcast:31 row_mask:0xc bank_mask:0xf
	s_nop 1
	v_readlane_b32 s20, v4, 63
	s_nop 1
	v_fma_f32 v6, s20, v16, v17
	v_rsq_f32_e32 v6, v6
	s_nop 0
	v_pk_mul_f32 v[68:69], v[68:69], v[6:7] op_sel_hi:[1,0]
	v_pk_mul_f32 v[70:71], v[70:71], v[6:7] op_sel_hi:[1,0]
	v_pk_mul_f32 v[72:73], v[72:73], v[6:7] op_sel_hi:[1,0]
	v_pk_mul_f32 v[74:75], v[74:75], v[6:7] op_sel_hi:[1,0]
	v_pk_mul_f32 v[76:77], v[76:77], v[6:7] op_sel_hi:[1,0]
	v_pk_mul_f32 v[78:79], v[78:79], v[6:7] op_sel_hi:[1,0]
	v_pk_mul_f32 v[80:81], v[80:81], v[6:7] op_sel_hi:[1,0]
	v_pk_mul_f32 v[82:83], v[82:83], v[6:7] op_sel_hi:[1,0]
	v_pk_mul_f32 v[68:69], v[68:69], v[20:21]
	v_pk_mul_f32 v[70:71], v[70:71], v[22:23]
	v_pk_mul_f32 v[72:73], v[72:73], v[24:25]
	v_pk_mul_f32 v[74:75], v[74:75], v[26:27]
	v_pk_mul_f32 v[76:77], v[76:77], v[28:29]
	v_pk_mul_f32 v[78:79], v[78:79], v[30:31]
	v_pk_mul_f32 v[80:81], v[80:81], v[32:33]
	v_pk_mul_f32 v[82:83], v[82:83], v[34:35]
	v_pk_fma_f32 v[68:69], v[68:69], v[52:53], v[36:37]
	v_pk_fma_f32 v[70:71], v[70:71], v[54:55], v[38:39]
	v_pk_fma_f32 v[72:73], v[72:73], v[56:57], v[40:41]
	v_pk_fma_f32 v[74:75], v[74:75], v[58:59], v[42:43]
	v_pk_fma_f32 v[76:77], v[76:77], v[60:61], v[44:45]
	v_pk_fma_f32 v[78:79], v[78:79], v[62:63], v[46:47]
	v_pk_fma_f32 v[80:81], v[80:81], v[64:65], v[48:49]
	v_pk_fma_f32 v[82:83], v[82:83], v[66:67], v[50:51]
	v_cvt_pk_bf16_f32 v232, v68, v69
	v_cvt_pk_bf16_f32 v233, v70, v71
	v_cvt_pk_bf16_f32 v234, v72, v73
	v_cvt_pk_bf16_f32 v235, v74, v75
	v_cvt_pk_bf16_f32 v236, v76, v77
	v_cvt_pk_bf16_f32 v237, v78, v79
	v_cvt_pk_bf16_f32 v238, v80, v81
	v_cvt_pk_bf16_f32 v239, v82, v83
	global_store_dwordx2 v1, v[232:233], s[10:11]
	global_store_dwordx2 v1, v[234:235], s[10:11] offset:512
	global_store_dwordx2 v1, v[236:237], s[10:11] offset:1024
	global_store_dwordx2 v1, v[238:239], s[10:11] offset:1536
	s_add_u32 s10, s10, 0x400000
	s_addc_u32 s11, s11, 0
	global_load_dwordx4 v[68:71], v0, s[8:9] nt
	global_load_dwordx4 v[72:75], v0, s[8:9] offset:1024 nt
	global_load_dwordx4 v[76:79], v0, s[8:9] offset:2048 nt
	global_load_dwordx4 v[80:83], v0, s[8:9] offset:3072 nt
	s_add_u32 s8, s8, 0x800000
	s_addc_u32 s9, s9, 0
	s_waitcnt vmcnt(24)
	v_pk_mul_f32 v[4:5], v[84:85], v[84:85]
	v_pk_fma_f32 v[4:5], v[86:87], v[86:87], v[4:5]
	v_pk_fma_f32 v[4:5], v[88:89], v[88:89], v[4:5]
	v_pk_fma_f32 v[4:5], v[90:91], v[90:91], v[4:5]
	v_pk_fma_f32 v[4:5], v[92:93], v[92:93], v[4:5]
	v_pk_fma_f32 v[4:5], v[94:95], v[94:95], v[4:5]
	v_pk_fma_f32 v[4:5], v[96:97], v[96:97], v[4:5]
	v_pk_fma_f32 v[4:5], v[98:99], v[98:99], v[4:5]
	v_add_f32_e32 v4, v4, v5
	s_nop 1
	v_add_f32_dpp v4, v4, v4 quad_perm:[1,0,3,2] row_mask:0xf bank_mask:0xf
	s_nop 1
	v_add_f32_dpp v4, v4, v4 quad_perm:[2,3,0,1] row_mask:0xf bank_mask:0xf
	s_nop 1
	v_add_f32_dpp v4, v4, v4 row_half_mirror row_mask:0xf bank_mask:0xf
	s_nop 1
	v_add_f32_dpp v4, v4, v4 row_mirror row_mask:0xf bank_mask:0xf
	s_nop 1
	v_add_f32_dpp v4, v4, v4 row_bcast:15 row_mask:0xa bank_mask:0xf
	s_nop 1
	v_add_f32_dpp v4, v4, v4 row_bcast:31 row_mask:0xc bank_mask:0xf
	s_nop 1
	v_readlane_b32 s20, v4, 63
	s_nop 1
	v_fma_f32 v6, s20, v16, v17
	v_rsq_f32_e32 v6, v6
	s_nop 0
	v_pk_mul_f32 v[84:85], v[84:85], v[6:7] op_sel_hi:[1,0]
	v_pk_mul_f32 v[86:87], v[86:87], v[6:7] op_sel_hi:[1,0]
	v_pk_mul_f32 v[88:89], v[88:89], v[6:7] op_sel_hi:[1,0]
	v_pk_mul_f32 v[90:91], v[90:91], v[6:7] op_sel_hi:[1,0]
	v_pk_mul_f32 v[92:93], v[92:93], v[6:7] op_sel_hi:[1,0]
	v_pk_mul_f32 v[94:95], v[94:95], v[6:7] op_sel_hi:[1,0]
	v_pk_mul_f32 v[96:97], v[96:97], v[6:7] op_sel_hi:[1,0]
	v_pk_mul_f32 v[98:99], v[98:99], v[6:7] op_sel_hi:[1,0]
	v_pk_mul_f32 v[84:85], v[84:85], v[20:21]
	v_pk_mul_f32 v[86:87], v[86:87], v[22:23]
	v_pk_mul_f32 v[88:89], v[88:89], v[24:25]
	v_pk_mul_f32 v[90:91], v[90:91], v[26:27]
	v_pk_mul_f32 v[92:93], v[92:93], v[28:29]
	v_pk_mul_f32 v[94:95], v[94:95], v[30:31]
	v_pk_mul_f32 v[96:97], v[96:97], v[32:33]
	v_pk_mul_f32 v[98:99], v[98:99], v[34:35]
	v_pk_fma_f32 v[84:85], v[84:85], v[52:53], v[36:37]
	v_pk_fma_f32 v[86:87], v[86:87], v[54:55], v[38:39]
	v_pk_fma_f32 v[88:89], v[88:89], v[56:57], v[40:41]
	v_pk_fma_f32 v[90:91], v[90:91], v[58:59], v[42:43]
	v_pk_fma_f32 v[92:93], v[92:93], v[60:61], v[44:45]
	v_pk_fma_f32 v[94:95], v[94:95], v[62:63], v[46:47]
	v_pk_fma_f32 v[96:97], v[96:97], v[64:65], v[48:49]
	v_pk_fma_f32 v[98:99], v[98:99], v[66:67], v[50:51]
	v_cvt_pk_bf16_f32 v240, v84, v85
	v_cvt_pk_bf16_f32 v241, v86, v87
	v_cvt_pk_bf16_f32 v242, v88, v89
	v_cvt_pk_bf16_f32 v243, v90, v91
	v_cvt_pk_bf16_f32 v244, v92, v93
	v_cvt_pk_bf16_f32 v245, v94, v95
	v_cvt_pk_bf16_f32 v246, v96, v97
	v_cvt_pk_bf16_f32 v247, v98, v99
	global_store_dwordx2 v1, v[240:241], s[10:11]
	global_store_dwordx2 v1, v[242:243], s[10:11] offset:512
	global_store_dwordx2 v1, v[244:245], s[10:11] offset:1024
	global_store_dwordx2 v1, v[246:247], s[10:11] offset:1536
	s_add_u32 s10, s10, 0x400000
	s_addc_u32 s11, s11, 0
	global_load_dwordx4 v[84:87], v0, s[8:9] nt
	global_load_dwordx4 v[88:91], v0, s[8:9] offset:1024 nt
	global_load_dwordx4 v[92:95], v0, s[8:9] offset:2048 nt
	global_load_dwordx4 v[96:99], v0, s[8:9] offset:3072 nt
	s_add_u32 s8, s8, 0x800000
	s_addc_u32 s9, s9, 0
	s_waitcnt vmcnt(28)
	v_pk_mul_f32 v[4:5], v[100:101], v[100:101]
	v_pk_fma_f32 v[4:5], v[102:103], v[102:103], v[4:5]
	v_pk_fma_f32 v[4:5], v[104:105], v[104:105], v[4:5]
	v_pk_fma_f32 v[4:5], v[106:107], v[106:107], v[4:5]
	v_pk_fma_f32 v[4:5], v[108:109], v[108:109], v[4:5]
	v_pk_fma_f32 v[4:5], v[110:111], v[110:111], v[4:5]
	v_pk_fma_f32 v[4:5], v[112:113], v[112:113], v[4:5]
	v_pk_fma_f32 v[4:5], v[114:115], v[114:115], v[4:5]
	v_add_f32_e32 v4, v4, v5
	s_nop 1
	v_add_f32_dpp v4, v4, v4 quad_perm:[1,0,3,2] row_mask:0xf bank_mask:0xf
	s_nop 1
	v_add_f32_dpp v4, v4, v4 quad_perm:[2,3,0,1] row_mask:0xf bank_mask:0xf
	s_nop 1
	v_add_f32_dpp v4, v4, v4 row_half_mirror row_mask:0xf bank_mask:0xf
	s_nop 1
	v_add_f32_dpp v4, v4, v4 row_mirror row_mask:0xf bank_mask:0xf
	s_nop 1
	v_add_f32_dpp v4, v4, v4 row_bcast:15 row_mask:0xa bank_mask:0xf
	s_nop 1
	v_add_f32_dpp v4, v4, v4 row_bcast:31 row_mask:0xc bank_mask:0xf
	s_nop 1
	v_readlane_b32 s20, v4, 63
	s_nop 1
	v_fma_f32 v6, s20, v16, v17
	v_rsq_f32_e32 v6, v6
	s_nop 0
	v_pk_mul_f32 v[100:101], v[100:101], v[6:7] op_sel_hi:[1,0]
	v_pk_mul_f32 v[102:103], v[102:103], v[6:7] op_sel_hi:[1,0]
	v_pk_mul_f32 v[104:105], v[104:105], v[6:7] op_sel_hi:[1,0]
	v_pk_mul_f32 v[106:107], v[106:107], v[6:7] op_sel_hi:[1,0]
	v_pk_mul_f32 v[108:109], v[108:109], v[6:7] op_sel_hi:[1,0]
	v_pk_mul_f32 v[110:111], v[110:111], v[6:7] op_sel_hi:[1,0]
	v_pk_mul_f32 v[112:113], v[112:113], v[6:7] op_sel_hi:[1,0]
	v_pk_mul_f32 v[114:115], v[114:115], v[6:7] op_sel_hi:[1,0]
	v_pk_mul_f32 v[100:101], v[100:101], v[20:21]
	v_pk_mul_f32 v[102:103], v[102:103], v[22:23]
	v_pk_mul_f32 v[104:105], v[104:105], v[24:25]
	v_pk_mul_f32 v[106:107], v[106:107], v[26:27]
	v_pk_mul_f32 v[108:109], v[108:109], v[28:29]
	v_pk_mul_f32 v[110:111], v[110:111], v[30:31]
	v_pk_mul_f32 v[112:113], v[112:113], v[32:33]
	v_pk_mul_f32 v[114:115], v[114:115], v[34:35]
	v_pk_fma_f32 v[100:101], v[100:101], v[52:53], v[36:37]
	v_pk_fma_f32 v[102:103], v[102:103], v[54:55], v[38:39]
	v_pk_fma_f32 v[104:105], v[104:105], v[56:57], v[40:41]
	v_pk_fma_f32 v[106:107], v[106:107], v[58:59], v[42:43]
	v_pk_fma_f32 v[108:109], v[108:109], v[60:61], v[44:45]
	v_pk_fma_f32 v[110:111], v[110:111], v[62:63], v[46:47]
	v_pk_fma_f32 v[112:113], v[112:113], v[64:65], v[48:49]
	v_pk_fma_f32 v[114:115], v[114:115], v[66:67], v[50:51]
	v_cvt_pk_bf16_f32 v232, v100, v101
	v_cvt_pk_bf16_f32 v233, v102, v103
	v_cvt_pk_bf16_f32 v234, v104, v105
	v_cvt_pk_bf16_f32 v235, v106, v107
	v_cvt_pk_bf16_f32 v236, v108, v109
	v_cvt_pk_bf16_f32 v237, v110, v111
	v_cvt_pk_bf16_f32 v238, v112, v113
	v_cvt_pk_bf16_f32 v239, v114, v115
	global_store_dwordx2 v1, v[232:233], s[10:11]
	global_store_dwordx2 v1, v[234:235], s[10:11] offset:512
	global_store_dwordx2 v1, v[236:237], s[10:11] offset:1024
	global_store_dwordx2 v1, v[238:239], s[10:11] offset:1536
	s_add_u32 s10, s10, 0x400000
	s_addc_u32 s11, s11, 0
	global_load_dwordx4 v[100:103], v0, s[8:9] nt
	global_load_dwordx4 v[104:107], v0, s[8:9] offset:1024 nt
	global_load_dwordx4 v[108:111], v0, s[8:9] offset:2048 nt
	global_load_dwordx4 v[112:115], v0, s[8:9] offset:3072 nt
	s_add_u32 s8, s8, 0x800000
	s_addc_u32 s9, s9, 0
	s_waitcnt vmcnt(32)
	v_pk_mul_f32 v[4:5], v[116:117], v[116:117]
	v_pk_fma_f32 v[4:5], v[118:119], v[118:119], v[4:5]
	v_pk_fma_f32 v[4:5], v[120:121], v[120:121], v[4:5]
	v_pk_fma_f32 v[4:5], v[122:123], v[122:123], v[4:5]
	v_pk_fma_f32 v[4:5], v[124:125], v[124:125], v[4:5]
	v_pk_fma_f32 v[4:5], v[126:127], v[126:127], v[4:5]
	v_pk_fma_f32 v[4:5], v[128:129], v[128:129], v[4:5]
	v_pk_fma_f32 v[4:5], v[130:131], v[130:131], v[4:5]
	v_add_f32_e32 v4, v4, v5
	s_nop 1
	v_add_f32_dpp v4, v4, v4 quad_perm:[1,0,3,2] row_mask:0xf bank_mask:0xf
	s_nop 1
	v_add_f32_dpp v4, v4, v4 quad_perm:[2,3,0,1] row_mask:0xf bank_mask:0xf
	s_nop 1
	v_add_f32_dpp v4, v4, v4 row_half_mirror row_mask:0xf bank_mask:0xf
	s_nop 1
	v_add_f32_dpp v4, v4, v4 row_mirror row_mask:0xf bank_mask:0xf
	s_nop 1
	v_add_f32_dpp v4, v4, v4 row_bcast:15 row_mask:0xa bank_mask:0xf
	s_nop 1
	v_add_f32_dpp v4, v4, v4 row_bcast:31 row_mask:0xc bank_mask:0xf
	s_nop 1
	v_readlane_b32 s20, v4, 63
	s_nop 1
	v_fma_f32 v6, s20, v16, v17
	v_rsq_f32_e32 v6, v6
	s_nop 0
	v_pk_mul_f32 v[116:117], v[116:117], v[6:7] op_sel_hi:[1,0]
	v_pk_mul_f32 v[118:119], v[118:119], v[6:7] op_sel_hi:[1,0]
	v_pk_mul_f32 v[120:121], v[120:121], v[6:7] op_sel_hi:[1,0]
	v_pk_mul_f32 v[122:123], v[122:123], v[6:7] op_sel_hi:[1,0]
	v_pk_mul_f32 v[124:125], v[124:125], v[6:7] op_sel_hi:[1,0]
	v_pk_mul_f32 v[126:127], v[126:127], v[6:7] op_sel_hi:[1,0]
	v_pk_mul_f32 v[128:129], v[128:129], v[6:7] op_sel_hi:[1,0]
	v_pk_mul_f32 v[130:131], v[130:131], v[6:7] op_sel_hi:[1,0]
	v_pk_mul_f32 v[116:117], v[116:117], v[20:21]
	v_pk_mul_f32 v[118:119], v[118:119], v[22:23]
	v_pk_mul_f32 v[120:121], v[120:121], v[24:25]
	v_pk_mul_f32 v[122:123], v[122:123], v[26:27]
	v_pk_mul_f32 v[124:125], v[124:125], v[28:29]
	v_pk_mul_f32 v[126:127], v[126:127], v[30:31]
	v_pk_mul_f32 v[128:129], v[128:129], v[32:33]
	v_pk_mul_f32 v[130:131], v[130:131], v[34:35]
	v_pk_fma_f32 v[116:117], v[116:117], v[52:53], v[36:37]
	v_pk_fma_f32 v[118:119], v[118:119], v[54:55], v[38:39]
	v_pk_fma_f32 v[120:121], v[120:121], v[56:57], v[40:41]
	v_pk_fma_f32 v[122:123], v[122:123], v[58:59], v[42:43]
	v_pk_fma_f32 v[124:125], v[124:125], v[60:61], v[44:45]
	v_pk_fma_f32 v[126:127], v[126:127], v[62:63], v[46:47]
	v_pk_fma_f32 v[128:129], v[128:129], v[64:65], v[48:49]
	v_pk_fma_f32 v[130:131], v[130:131], v[66:67], v[50:51]
	v_cvt_pk_bf16_f32 v240, v116, v117
	v_cvt_pk_bf16_f32 v241, v118, v119
	v_cvt_pk_bf16_f32 v242, v120, v121
	v_cvt_pk_bf16_f32 v243, v122, v123
	v_cvt_pk_bf16_f32 v244, v124, v125
	v_cvt_pk_bf16_f32 v245, v126, v127
	v_cvt_pk_bf16_f32 v246, v128, v129
	v_cvt_pk_bf16_f32 v247, v130, v131
	global_store_dwordx2 v1, v[240:241], s[10:11]
	global_store_dwordx2 v1, v[242:243], s[10:11] offset:512
	global_store_dwordx2 v1, v[244:245], s[10:11] offset:1024
	global_store_dwordx2 v1, v[246:247], s[10:11] offset:1536
	s_add_u32 s10, s10, 0x400000
	s_addc_u32 s11, s11, 0
	global_load_dwordx4 v[116:119], v0, s[8:9] nt
	global_load_dwordx4 v[120:123], v0, s[8:9] offset:1024 nt
	global_load_dwordx4 v[124:127], v0, s[8:9] offset:2048 nt
	global_load_dwordx4 v[128:131], v0, s[8:9] offset:3072 nt
	s_add_u32 s8, s8, 0x800000
	s_addc_u32 s9, s9, 0
	s_waitcnt vmcnt(24)
	v_pk_add_f32 v[164:165], v[164:165], v[18:19]
	v_pk_add_f32 v[166:167], v[166:167], v[18:19]
	v_pk_add_f32 v[168:169], v[168:169], v[18:19]
	v_pk_add_f32 v[170:171], v[170:171], v[18:19]
	v_pk_add_f32 v[172:173], v[172:173], v[18:19]
	v_pk_add_f32 v[174:175], v[174:175], v[18:19]
	v_pk_add_f32 v[176:177], v[176:177], v[18:19]
	v_pk_add_f32 v[178:179], v[178:179], v[18:19]
	s_add_u32 s14, s12, 0xc000
	s_addc_u32 s15, s13, 0
	s_add_u32 s16, s14, 0x1000
	s_addc_u32 s17, s15, 0
	global_load_dwordx4 v[36:39], v0, s[14:15]
	global_load_dwordx4 v[40:43], v0, s[14:15] offset:1024
	global_load_dwordx4 v[44:47], v0, s[14:15] offset:2048
	global_load_dwordx4 v[48:51], v0, s[14:15] offset:3072
	global_load_dwordx4 v[52:55], v0, s[16:17]
	global_load_dwordx4 v[56:59], v0, s[16:17] offset:1024
	global_load_dwordx4 v[60:63], v0, s[16:17] offset:2048
	global_load_dwordx4 v[64:67], v0, s[16:17] offset:3072
	v_pk_mul_f32 v[4:5], v[68:69], v[68:69]
	v_pk_fma_f32 v[4:5], v[70:71], v[70:71], v[4:5]
	v_pk_fma_f32 v[4:5], v[72:73], v[72:73], v[4:5]
	v_pk_fma_f32 v[4:5], v[74:75], v[74:75], v[4:5]
	v_pk_fma_f32 v[4:5], v[76:77], v[76:77], v[4:5]
	v_pk_fma_f32 v[4:5], v[78:79], v[78:79], v[4:5]
	v_pk_fma_f32 v[4:5], v[80:81], v[80:81], v[4:5]
	v_pk_fma_f32 v[4:5], v[82:83], v[82:83], v[4:5]
	v_add_f32_e32 v4, v4, v5
	s_nop 1
	v_add_f32_dpp v4, v4, v4 quad_perm:[1,0,3,2] row_mask:0xf bank_mask:0xf
	s_nop 1
	v_add_f32_dpp v4, v4, v4 quad_perm:[2,3,0,1] row_mask:0xf bank_mask:0xf
	s_nop 1
	v_add_f32_dpp v4, v4, v4 row_half_mirror row_mask:0xf bank_mask:0xf
	s_nop 1
	v_add_f32_dpp v4, v4, v4 row_mirror row_mask:0xf bank_mask:0xf
	s_nop 1
	v_add_f32_dpp v4, v4, v4 row_bcast:15 row_mask:0xa bank_mask:0xf
	s_nop 1
	v_add_f32_dpp v4, v4, v4 row_bcast:31 row_mask:0xc bank_mask:0xf
	s_nop 1
	v_readlane_b32 s20, v4, 63
	s_nop 1
	v_fma_f32 v6, s20, v16, v17
	v_rsq_f32_e32 v6, v6
	s_nop 0
	v_pk_mul_f32 v[68:69], v[68:69], v[6:7] op_sel_hi:[1,0]
	v_pk_mul_f32 v[70:71], v[70:71], v[6:7] op_sel_hi:[1,0]
	v_pk_mul_f32 v[72:73], v[72:73], v[6:7] op_sel_hi:[1,0]
	v_pk_mul_f32 v[74:75], v[74:75], v[6:7] op_sel_hi:[1,0]
	v_pk_mul_f32 v[76:77], v[76:77], v[6:7] op_sel_hi:[1,0]
	v_pk_mul_f32 v[78:79], v[78:79], v[6:7] op_sel_hi:[1,0]
	v_pk_mul_f32 v[80:81], v[80:81], v[6:7] op_sel_hi:[1,0]
	v_pk_mul_f32 v[82:83], v[82:83], v[6:7] op_sel_hi:[1,0]
	v_pk_mul_f32 v[68:69], v[68:69], v[20:21]
	v_pk_mul_f32 v[70:71], v[70:71], v[22:23]
	v_pk_mul_f32 v[72:73], v[72:73], v[24:25]
	v_pk_mul_f32 v[74:75], v[74:75], v[26:27]
	v_pk_mul_f32 v[76:77], v[76:77], v[28:29]
	v_pk_mul_f32 v[78:79], v[78:79], v[30:31]
	v_pk_mul_f32 v[80:81], v[80:81], v[32:33]
	v_pk_mul_f32 v[82:83], v[82:83], v[34:35]
	v_pk_fma_f32 v[68:69], v[68:69], v[164:165], v[148:149]
	v_pk_fma_f32 v[70:71], v[70:71], v[166:167], v[150:151]
	v_pk_fma_f32 v[72:73], v[72:73], v[168:169], v[152:153]
	v_pk_fma_f32 v[74:75], v[74:75], v[170:171], v[154:155]
	v_pk_fma_f32 v[76:77], v[76:77], v[172:173], v[156:157]
	v_pk_fma_f32 v[78:79], v[78:79], v[174:175], v[158:159]
	v_pk_fma_f32 v[80:81], v[80:81], v[176:177], v[160:161]
	v_pk_fma_f32 v[82:83], v[82:83], v[178:179], v[162:163]
	v_cvt_pk_bf16_f32 v232, v68, v69
	v_cvt_pk_bf16_f32 v233, v70, v71
	v_cvt_pk_bf16_f32 v234, v72, v73
	v_cvt_pk_bf16_f32 v235, v74, v75
	v_cvt_pk_bf16_f32 v236, v76, v77
	v_cvt_pk_bf16_f32 v237, v78, v79
	v_cvt_pk_bf16_f32 v238, v80, v81
	v_cvt_pk_bf16_f32 v239, v82, v83
	global_store_dwordx2 v1, v[232:233], s[10:11]
	global_store_dwordx2 v1, v[234:235], s[10:11] offset:512
	global_store_dwordx2 v1, v[236:237], s[10:11] offset:1024
	global_store_dwordx2 v1, v[238:239], s[10:11] offset:1536
	s_add_u32 s10, s10, 0x400000
	s_addc_u32 s11, s11, 0
	global_load_dwordx4 v[68:71], v0, s[8:9] nt
	global_load_dwordx4 v[72:75], v0, s[8:9] offset:1024 nt
	global_load_dwordx4 v[76:79], v0, s[8:9] offset:2048 nt
	global_load_dwordx4 v[80:83], v0, s[8:9] offset:3072 nt
	s_add_u32 s8, s8, 0x800000
	s_addc_u32 s9, s9, 0
	s_waitcnt vmcnt(32)
	v_pk_mul_f32 v[4:5], v[84:85], v[84:85]
	v_pk_fma_f32 v[4:5], v[86:87], v[86:87], v[4:5]
	v_pk_fma_f32 v[4:5], v[88:89], v[88:89], v[4:5]
	v_pk_fma_f32 v[4:5], v[90:91], v[90:91], v[4:5]
	v_pk_fma_f32 v[4:5], v[92:93], v[92:93], v[4:5]
	v_pk_fma_f32 v[4:5], v[94:95], v[94:95], v[4:5]
	v_pk_fma_f32 v[4:5], v[96:97], v[96:97], v[4:5]
	v_pk_fma_f32 v[4:5], v[98:99], v[98:99], v[4:5]
	v_add_f32_e32 v4, v4, v5
	s_nop 1
	v_add_f32_dpp v4, v4, v4 quad_perm:[1,0,3,2] row_mask:0xf bank_mask:0xf
	s_nop 1
	v_add_f32_dpp v4, v4, v4 quad_perm:[2,3,0,1] row_mask:0xf bank_mask:0xf
	s_nop 1
	v_add_f32_dpp v4, v4, v4 row_half_mirror row_mask:0xf bank_mask:0xf
	s_nop 1
	v_add_f32_dpp v4, v4, v4 row_mirror row_mask:0xf bank_mask:0xf
	s_nop 1
	v_add_f32_dpp v4, v4, v4 row_bcast:15 row_mask:0xa bank_mask:0xf
	s_nop 1
	v_add_f32_dpp v4, v4, v4 row_bcast:31 row_mask:0xc bank_mask:0xf
	s_nop 1
	v_readlane_b32 s20, v4, 63
	s_nop 1
	v_fma_f32 v6, s20, v16, v17
	v_rsq_f32_e32 v6, v6
	s_nop 0
	v_pk_mul_f32 v[84:85], v[84:85], v[6:7] op_sel_hi:[1,0]
	v_pk_mul_f32 v[86:87], v[86:87], v[6:7] op_sel_hi:[1,0]
	v_pk_mul_f32 v[88:89], v[88:89], v[6:7] op_sel_hi:[1,0]
	v_pk_mul_f32 v[90:91], v[90:91], v[6:7] op_sel_hi:[1,0]
	v_pk_mul_f32 v[92:93], v[92:93], v[6:7] op_sel_hi:[1,0]
	v_pk_mul_f32 v[94:95], v[94:95], v[6:7] op_sel_hi:[1,0]
	v_pk_mul_f32 v[96:97], v[96:97], v[6:7] op_sel_hi:[1,0]
	v_pk_mul_f32 v[98:99], v[98:99], v[6:7] op_sel_hi:[1,0]
	v_pk_mul_f32 v[84:85], v[84:85], v[20:21]
	v_pk_mul_f32 v[86:87], v[86:87], v[22:23]
	v_pk_mul_f32 v[88:89], v[88:89], v[24:25]
	v_pk_mul_f32 v[90:91], v[90:91], v[26:27]
	v_pk_mul_f32 v[92:93], v[92:93], v[28:29]
	v_pk_mul_f32 v[94:95], v[94:95], v[30:31]
	v_pk_mul_f32 v[96:97], v[96:97], v[32:33]
	v_pk_mul_f32 v[98:99], v[98:99], v[34:35]
	v_pk_fma_f32 v[84:85], v[84:85], v[164:165], v[148:149]
	v_pk_fma_f32 v[86:87], v[86:87], v[166:167], v[150:151]
	v_pk_fma_f32 v[88:89], v[88:89], v[168:169], v[152:153]
	v_pk_fma_f32 v[90:91], v[90:91], v[170:171], v[154:155]
	v_pk_fma_f32 v[92:93], v[92:93], v[172:173], v[156:157]
	v_pk_fma_f32 v[94:95], v[94:95], v[174:175], v[158:159]
	v_pk_fma_f32 v[96:97], v[96:97], v[176:177], v[160:161]
	v_pk_fma_f32 v[98:99], v[98:99], v[178:179], v[162:163]
	v_cvt_pk_bf16_f32 v240, v84, v85
	v_cvt_pk_bf16_f32 v241, v86, v87
	v_cvt_pk_bf16_f32 v242, v88, v89
	v_cvt_pk_bf16_f32 v243, v90, v91
	v_cvt_pk_bf16_f32 v244, v92, v93
	v_cvt_pk_bf16_f32 v245, v94, v95
	v_cvt_pk_bf16_f32 v246, v96, v97
	v_cvt_pk_bf16_f32 v247, v98, v99
	global_store_dwordx2 v1, v[240:241], s[10:11]
	global_store_dwordx2 v1, v[242:243], s[10:11] offset:512
	global_store_dwordx2 v1, v[244:245], s[10:11] offset:1024
	global_store_dwordx2 v1, v[246:247], s[10:11] offset:1536
	s_add_u32 s10, s10, 0x400000
	s_addc_u32 s11, s11, 0
	global_load_dwordx4 v[84:87], v0, s[8:9] nt
	global_load_dwordx4 v[88:91], v0, s[8:9] offset:1024 nt
	global_load_dwordx4 v[92:95], v0, s[8:9] offset:2048 nt
	global_load_dwordx4 v[96:99], v0, s[8:9] offset:3072 nt
	s_add_u32 s8, s8, 0x800000
	s_addc_u32 s9, s9, 0
	s_waitcnt vmcnt(32)
	v_pk_mul_f32 v[4:5], v[100:101], v[100:101]
	v_pk_fma_f32 v[4:5], v[102:103], v[102:103], v[4:5]
	v_pk_fma_f32 v[4:5], v[104:105], v[104:105], v[4:5]
	v_pk_fma_f32 v[4:5], v[106:107], v[106:107], v[4:5]
	v_pk_fma_f32 v[4:5], v[108:109], v[108:109], v[4:5]
	v_pk_fma_f32 v[4:5], v[110:111], v[110:111], v[4:5]
	v_pk_fma_f32 v[4:5], v[112:113], v[112:113], v[4:5]
	v_pk_fma_f32 v[4:5], v[114:115], v[114:115], v[4:5]
	v_add_f32_e32 v4, v4, v5
	s_nop 1
	v_add_f32_dpp v4, v4, v4 quad_perm:[1,0,3,2] row_mask:0xf bank_mask:0xf
	s_nop 1
	v_add_f32_dpp v4, v4, v4 quad_perm:[2,3,0,1] row_mask:0xf bank_mask:0xf
	s_nop 1
	v_add_f32_dpp v4, v4, v4 row_half_mirror row_mask:0xf bank_mask:0xf
	s_nop 1
	v_add_f32_dpp v4, v4, v4 row_mirror row_mask:0xf bank_mask:0xf
	s_nop 1
	v_add_f32_dpp v4, v4, v4 row_bcast:15 row_mask:0xa bank_mask:0xf
	s_nop 1
	v_add_f32_dpp v4, v4, v4 row_bcast:31 row_mask:0xc bank_mask:0xf
	s_nop 1
	v_readlane_b32 s20, v4, 63
	s_nop 1
	v_fma_f32 v6, s20, v16, v17
	v_rsq_f32_e32 v6, v6
	s_nop 0
	v_pk_mul_f32 v[100:101], v[100:101], v[6:7] op_sel_hi:[1,0]
	v_pk_mul_f32 v[102:103], v[102:103], v[6:7] op_sel_hi:[1,0]
	v_pk_mul_f32 v[104:105], v[104:105], v[6:7] op_sel_hi:[1,0]
	v_pk_mul_f32 v[106:107], v[106:107], v[6:7] op_sel_hi:[1,0]
	v_pk_mul_f32 v[108:109], v[108:109], v[6:7] op_sel_hi:[1,0]
	v_pk_mul_f32 v[110:111], v[110:111], v[6:7] op_sel_hi:[1,0]
	v_pk_mul_f32 v[112:113], v[112:113], v[6:7] op_sel_hi:[1,0]
	v_pk_mul_f32 v[114:115], v[114:115], v[6:7] op_sel_hi:[1,0]
	v_pk_mul_f32 v[100:101], v[100:101], v[20:21]
	v_pk_mul_f32 v[102:103], v[102:103], v[22:23]
	v_pk_mul_f32 v[104:105], v[104:105], v[24:25]
	v_pk_mul_f32 v[106:107], v[106:107], v[26:27]
	v_pk_mul_f32 v[108:109], v[108:109], v[28:29]
	v_pk_mul_f32 v[110:111], v[110:111], v[30:31]
	v_pk_mul_f32 v[112:113], v[112:113], v[32:33]
	v_pk_mul_f32 v[114:115], v[114:115], v[34:35]
	v_pk_fma_f32 v[100:101], v[100:101], v[164:165], v[148:149]
	v_pk_fma_f32 v[102:103], v[102:103], v[166:167], v[150:151]
	v_pk_fma_f32 v[104:105], v[104:105], v[168:169], v[152:153]
	v_pk_fma_f32 v[106:107], v[106:107], v[170:171], v[154:155]
	v_pk_fma_f32 v[108:109], v[108:109], v[172:173], v[156:157]
	v_pk_fma_f32 v[110:111], v[110:111], v[174:175], v[158:159]
	v_pk_fma_f32 v[112:113], v[112:113], v[176:177], v[160:161]
	v_pk_fma_f32 v[114:115], v[114:115], v[178:179], v[162:163]
	v_cvt_pk_bf16_f32 v232, v100, v101
	v_cvt_pk_bf16_f32 v233, v102, v103
	v_cvt_pk_bf16_f32 v234, v104, v105
	v_cvt_pk_bf16_f32 v235, v106, v107
	v_cvt_pk_bf16_f32 v236, v108, v109
	v_cvt_pk_bf16_f32 v237, v110, v111
	v_cvt_pk_bf16_f32 v238, v112, v113
	v_cvt_pk_bf16_f32 v239, v114, v115
	global_store_dwordx2 v1, v[232:233], s[10:11]
	global_store_dwordx2 v1, v[234:235], s[10:11] offset:512
	global_store_dwordx2 v1, v[236:237], s[10:11] offset:1024
	global_store_dwordx2 v1, v[238:239], s[10:11] offset:1536
	s_add_u32 s10, s10, 0x400000
	s_addc_u32 s11, s11, 0
	global_load_dwordx4 v[100:103], v0, s[8:9] nt
	global_load_dwordx4 v[104:107], v0, s[8:9] offset:1024 nt
	global_load_dwordx4 v[108:111], v0, s[8:9] offset:2048 nt
	global_load_dwordx4 v[112:115], v0, s[8:9] offset:3072 nt
	s_add_u32 s8, s8, 0x800000
	s_addc_u32 s9, s9, 0
	s_waitcnt vmcnt(32)
	v_pk_mul_f32 v[4:5], v[116:117], v[116:117]
	v_pk_fma_f32 v[4:5], v[118:119], v[118:119], v[4:5]
	v_pk_fma_f32 v[4:5], v[120:121], v[120:121], v[4:5]
	v_pk_fma_f32 v[4:5], v[122:123], v[122:123], v[4:5]
	v_pk_fma_f32 v[4:5], v[124:125], v[124:125], v[4:5]
	v_pk_fma_f32 v[4:5], v[126:127], v[126:127], v[4:5]
	v_pk_fma_f32 v[4:5], v[128:129], v[128:129], v[4:5]
	v_pk_fma_f32 v[4:5], v[130:131], v[130:131], v[4:5]
	v_add_f32_e32 v4, v4, v5
	s_nop 1
	v_add_f32_dpp v4, v4, v4 quad_perm:[1,0,3,2] row_mask:0xf bank_mask:0xf
	s_nop 1
	v_add_f32_dpp v4, v4, v4 quad_perm:[2,3,0,1] row_mask:0xf bank_mask:0xf
	s_nop 1
	v_add_f32_dpp v4, v4, v4 row_half_mirror row_mask:0xf bank_mask:0xf
	s_nop 1
	v_add_f32_dpp v4, v4, v4 row_mirror row_mask:0xf bank_mask:0xf
	s_nop 1
	v_add_f32_dpp v4, v4, v4 row_bcast:15 row_mask:0xa bank_mask:0xf
	s_nop 1
	v_add_f32_dpp v4, v4, v4 row_bcast:31 row_mask:0xc bank_mask:0xf
	s_nop 1
	v_readlane_b32 s20, v4, 63
	s_nop 1
	v_fma_f32 v6, s20, v16, v17
	v_rsq_f32_e32 v6, v6
	s_nop 0
	v_pk_mul_f32 v[116:117], v[116:117], v[6:7] op_sel_hi:[1,0]
	v_pk_mul_f32 v[118:119], v[118:119], v[6:7] op_sel_hi:[1,0]
	v_pk_mul_f32 v[120:121], v[120:121], v[6:7] op_sel_hi:[1,0]
	v_pk_mul_f32 v[122:123], v[122:123], v[6:7] op_sel_hi:[1,0]
	v_pk_mul_f32 v[124:125], v[124:125], v[6:7] op_sel_hi:[1,0]
	v_pk_mul_f32 v[126:127], v[126:127], v[6:7] op_sel_hi:[1,0]
	v_pk_mul_f32 v[128:129], v[128:129], v[6:7] op_sel_hi:[1,0]
	v_pk_mul_f32 v[130:131], v[130:131], v[6:7] op_sel_hi:[1,0]
	v_pk_mul_f32 v[116:117], v[116:117], v[20:21]
	v_pk_mul_f32 v[118:119], v[118:119], v[22:23]
	v_pk_mul_f32 v[120:121], v[120:121], v[24:25]
	v_pk_mul_f32 v[122:123], v[122:123], v[26:27]
	v_pk_mul_f32 v[124:125], v[124:125], v[28:29]
	v_pk_mul_f32 v[126:127], v[126:127], v[30:31]
	v_pk_mul_f32 v[128:129], v[128:129], v[32:33]
	v_pk_mul_f32 v[130:131], v[130:131], v[34:35]
	v_pk_fma_f32 v[116:117], v[116:117], v[164:165], v[148:149]
	v_pk_fma_f32 v[118:119], v[118:119], v[166:167], v[150:151]
	v_pk_fma_f32 v[120:121], v[120:121], v[168:169], v[152:153]
	v_pk_fma_f32 v[122:123], v[122:123], v[170:171], v[154:155]
	v_pk_fma_f32 v[124:125], v[124:125], v[172:173], v[156:157]
	v_pk_fma_f32 v[126:127], v[126:127], v[174:175], v[158:159]
	v_pk_fma_f32 v[128:129], v[128:129], v[176:177], v[160:161]
	v_pk_fma_f32 v[130:131], v[130:131], v[178:179], v[162:163]
	v_cvt_pk_bf16_f32 v240, v116, v117
	v_cvt_pk_bf16_f32 v241, v118, v119
	v_cvt_pk_bf16_f32 v242, v120, v121
	v_cvt_pk_bf16_f32 v243, v122, v123
	v_cvt_pk_bf16_f32 v244, v124, v125
	v_cvt_pk_bf16_f32 v245, v126, v127
	v_cvt_pk_bf16_f32 v246, v128, v129
	v_cvt_pk_bf16_f32 v247, v130, v131
	global_store_dwordx2 v1, v[240:241], s[10:11]
	global_store_dwordx2 v1, v[242:243], s[10:11] offset:512
	global_store_dwordx2 v1, v[244:245], s[10:11] offset:1024
	global_store_dwordx2 v1, v[246:247], s[10:11] offset:1536
	s_add_u32 s10, s10, 0x400000
	s_addc_u32 s11, s11, 0
	global_load_dwordx4 v[116:119], v0, s[8:9] nt
	global_load_dwordx4 v[120:123], v0, s[8:9] offset:1024 nt
	global_load_dwordx4 v[124:127], v0, s[8:9] offset:2048 nt
	global_load_dwordx4 v[128:131], v0, s[8:9] offset:3072 nt
	s_add_u32 s8, s8, 0x800000
	s_addc_u32 s9, s9, 0
	s_waitcnt vmcnt(24)
	v_pk_add_f32 v[52:53], v[52:53], v[18:19]
	v_pk_add_f32 v[54:55], v[54:55], v[18:19]
	v_pk_add_f32 v[56:57], v[56:57], v[18:19]
	v_pk_add_f32 v[58:59], v[58:59], v[18:19]
	v_pk_add_f32 v[60:61], v[60:61], v[18:19]
	v_pk_add_f32 v[62:63], v[62:63], v[18:19]
	v_pk_add_f32 v[64:65], v[64:65], v[18:19]
	v_pk_add_f32 v[66:67], v[66:67], v[18:19]
	s_add_u32 s14, s12, 0x12000
	s_addc_u32 s15, s13, 0
	s_add_u32 s16, s14, 0x1000
	s_addc_u32 s17, s15, 0
	global_load_dwordx4 v[148:151], v0, s[14:15]
	global_load_dwordx4 v[152:155], v0, s[14:15] offset:1024
	global_load_dwordx4 v[156:159], v0, s[14:15] offset:2048
	global_load_dwordx4 v[160:163], v0, s[14:15] offset:3072
	global_load_dwordx4 v[164:167], v0, s[16:17]
	global_load_dwordx4 v[168:171], v0, s[16:17] offset:1024
	global_load_dwordx4 v[172:175], v0, s[16:17] offset:2048
	global_load_dwordx4 v[176:179], v0, s[16:17] offset:3072
	v_pk_mul_f32 v[4:5], v[68:69], v[68:69]
	v_pk_fma_f32 v[4:5], v[70:71], v[70:71], v[4:5]
	v_pk_fma_f32 v[4:5], v[72:73], v[72:73], v[4:5]
	v_pk_fma_f32 v[4:5], v[74:75], v[74:75], v[4:5]
	v_pk_fma_f32 v[4:5], v[76:77], v[76:77], v[4:5]
	v_pk_fma_f32 v[4:5], v[78:79], v[78:79], v[4:5]
	v_pk_fma_f32 v[4:5], v[80:81], v[80:81], v[4:5]
	v_pk_fma_f32 v[4:5], v[82:83], v[82:83], v[4:5]
	v_add_f32_e32 v4, v4, v5
	s_nop 1
	v_add_f32_dpp v4, v4, v4 quad_perm:[1,0,3,2] row_mask:0xf bank_mask:0xf
	s_nop 1
	v_add_f32_dpp v4, v4, v4 quad_perm:[2,3,0,1] row_mask:0xf bank_mask:0xf
	s_nop 1
	v_add_f32_dpp v4, v4, v4 row_half_mirror row_mask:0xf bank_mask:0xf
	s_nop 1
	v_add_f32_dpp v4, v4, v4 row_mirror row_mask:0xf bank_mask:0xf
	s_nop 1
	v_add_f32_dpp v4, v4, v4 row_bcast:15 row_mask:0xa bank_mask:0xf
	s_nop 1
	v_add_f32_dpp v4, v4, v4 row_bcast:31 row_mask:0xc bank_mask:0xf
	s_nop 1
	v_readlane_b32 s20, v4, 63
	s_nop 1
	v_fma_f32 v6, s20, v16, v17
	v_rsq_f32_e32 v6, v6
	s_nop 0
	v_pk_mul_f32 v[68:69], v[68:69], v[6:7] op_sel_hi:[1,0]
	v_pk_mul_f32 v[70:71], v[70:71], v[6:7] op_sel_hi:[1,0]
	v_pk_mul_f32 v[72:73], v[72:73], v[6:7] op_sel_hi:[1,0]
	v_pk_mul_f32 v[74:75], v[74:75], v[6:7] op_sel_hi:[1,0]
	v_pk_mul_f32 v[76:77], v[76:77], v[6:7] op_sel_hi:[1,0]
	v_pk_mul_f32 v[78:79], v[78:79], v[6:7] op_sel_hi:[1,0]
	v_pk_mul_f32 v[80:81], v[80:81], v[6:7] op_sel_hi:[1,0]
	v_pk_mul_f32 v[82:83], v[82:83], v[6:7] op_sel_hi:[1,0]
	v_pk_mul_f32 v[68:69], v[68:69], v[20:21]
	v_pk_mul_f32 v[70:71], v[70:71], v[22:23]
	v_pk_mul_f32 v[72:73], v[72:73], v[24:25]
	v_pk_mul_f32 v[74:75], v[74:75], v[26:27]
	v_pk_mul_f32 v[76:77], v[76:77], v[28:29]
	v_pk_mul_f32 v[78:79], v[78:79], v[30:31]
	v_pk_mul_f32 v[80:81], v[80:81], v[32:33]
	v_pk_mul_f32 v[82:83], v[82:83], v[34:35]
	v_pk_fma_f32 v[68:69], v[68:69], v[52:53], v[36:37]
	v_pk_fma_f32 v[70:71], v[70:71], v[54:55], v[38:39]
	v_pk_fma_f32 v[72:73], v[72:73], v[56:57], v[40:41]
	v_pk_fma_f32 v[74:75], v[74:75], v[58:59], v[42:43]
	v_pk_fma_f32 v[76:77], v[76:77], v[60:61], v[44:45]
	v_pk_fma_f32 v[78:79], v[78:79], v[62:63], v[46:47]
	v_pk_fma_f32 v[80:81], v[80:81], v[64:65], v[48:49]
	v_pk_fma_f32 v[82:83], v[82:83], v[66:67], v[50:51]
	v_cvt_pk_bf16_f32 v232, v68, v69
	v_cvt_pk_bf16_f32 v233, v70, v71
	v_cvt_pk_bf16_f32 v234, v72, v73
	v_cvt_pk_bf16_f32 v235, v74, v75
	v_cvt_pk_bf16_f32 v236, v76, v77
	v_cvt_pk_bf16_f32 v237, v78, v79
	v_cvt_pk_bf16_f32 v238, v80, v81
	v_cvt_pk_bf16_f32 v239, v82, v83
	global_store_dwordx2 v1, v[232:233], s[10:11]
	global_store_dwordx2 v1, v[234:235], s[10:11] offset:512
	global_store_dwordx2 v1, v[236:237], s[10:11] offset:1024
	global_store_dwordx2 v1, v[238:239], s[10:11] offset:1536
	s_add_u32 s10, s10, 0x400000
	s_addc_u32 s11, s11, 0
	global_load_dwordx4 v[68:71], v0, s[8:9] nt
	global_load_dwordx4 v[72:75], v0, s[8:9] offset:1024 nt
	global_load_dwordx4 v[76:79], v0, s[8:9] offset:2048 nt
	global_load_dwordx4 v[80:83], v0, s[8:9] offset:3072 nt
	s_add_u32 s8, s8, 0x800000
	s_addc_u32 s9, s9, 0
	s_waitcnt vmcnt(32)
	v_pk_mul_f32 v[4:5], v[84:85], v[84:85]
	v_pk_fma_f32 v[4:5], v[86:87], v[86:87], v[4:5]
	v_pk_fma_f32 v[4:5], v[88:89], v[88:89], v[4:5]
	v_pk_fma_f32 v[4:5], v[90:91], v[90:91], v[4:5]
	v_pk_fma_f32 v[4:5], v[92:93], v[92:93], v[4:5]
	v_pk_fma_f32 v[4:5], v[94:95], v[94:95], v[4:5]
	v_pk_fma_f32 v[4:5], v[96:97], v[96:97], v[4:5]
	v_pk_fma_f32 v[4:5], v[98:99], v[98:99], v[4:5]
	v_add_f32_e32 v4, v4, v5
	s_nop 1
	v_add_f32_dpp v4, v4, v4 quad_perm:[1,0,3,2] row_mask:0xf bank_mask:0xf
	s_nop 1
	v_add_f32_dpp v4, v4, v4 quad_perm:[2,3,0,1] row_mask:0xf bank_mask:0xf
	s_nop 1
	v_add_f32_dpp v4, v4, v4 row_half_mirror row_mask:0xf bank_mask:0xf
	s_nop 1
	v_add_f32_dpp v4, v4, v4 row_mirror row_mask:0xf bank_mask:0xf
	s_nop 1
	v_add_f32_dpp v4, v4, v4 row_bcast:15 row_mask:0xa bank_mask:0xf
	s_nop 1
	v_add_f32_dpp v4, v4, v4 row_bcast:31 row_mask:0xc bank_mask:0xf
	s_nop 1
	v_readlane_b32 s20, v4, 63
	s_nop 1
	v_fma_f32 v6, s20, v16, v17
	v_rsq_f32_e32 v6, v6
	s_nop 0
	v_pk_mul_f32 v[84:85], v[84:85], v[6:7] op_sel_hi:[1,0]
	v_pk_mul_f32 v[86:87], v[86:87], v[6:7] op_sel_hi:[1,0]
	v_pk_mul_f32 v[88:89], v[88:89], v[6:7] op_sel_hi:[1,0]
	v_pk_mul_f32 v[90:91], v[90:91], v[6:7] op_sel_hi:[1,0]
	v_pk_mul_f32 v[92:93], v[92:93], v[6:7] op_sel_hi:[1,0]
	v_pk_mul_f32 v[94:95], v[94:95], v[6:7] op_sel_hi:[1,0]
	v_pk_mul_f32 v[96:97], v[96:97], v[6:7] op_sel_hi:[1,0]
	v_pk_mul_f32 v[98:99], v[98:99], v[6:7] op_sel_hi:[1,0]
	v_pk_mul_f32 v[84:85], v[84:85], v[20:21]
	v_pk_mul_f32 v[86:87], v[86:87], v[22:23]
	v_pk_mul_f32 v[88:89], v[88:89], v[24:25]
	v_pk_mul_f32 v[90:91], v[90:91], v[26:27]
	v_pk_mul_f32 v[92:93], v[92:93], v[28:29]
	v_pk_mul_f32 v[94:95], v[94:95], v[30:31]
	v_pk_mul_f32 v[96:97], v[96:97], v[32:33]
	v_pk_mul_f32 v[98:99], v[98:99], v[34:35]
	v_pk_fma_f32 v[84:85], v[84:85], v[52:53], v[36:37]
	v_pk_fma_f32 v[86:87], v[86:87], v[54:55], v[38:39]
	v_pk_fma_f32 v[88:89], v[88:89], v[56:57], v[40:41]
	v_pk_fma_f32 v[90:91], v[90:91], v[58:59], v[42:43]
	v_pk_fma_f32 v[92:93], v[92:93], v[60:61], v[44:45]
	v_pk_fma_f32 v[94:95], v[94:95], v[62:63], v[46:47]
	v_pk_fma_f32 v[96:97], v[96:97], v[64:65], v[48:49]
	v_pk_fma_f32 v[98:99], v[98:99], v[66:67], v[50:51]
	v_cvt_pk_bf16_f32 v240, v84, v85
	v_cvt_pk_bf16_f32 v241, v86, v87
	v_cvt_pk_bf16_f32 v242, v88, v89
	v_cvt_pk_bf16_f32 v243, v90, v91
	v_cvt_pk_bf16_f32 v244, v92, v93
	v_cvt_pk_bf16_f32 v245, v94, v95
	v_cvt_pk_bf16_f32 v246, v96, v97
	v_cvt_pk_bf16_f32 v247, v98, v99
	global_store_dwordx2 v1, v[240:241], s[10:11]
	global_store_dwordx2 v1, v[242:243], s[10:11] offset:512
	global_store_dwordx2 v1, v[244:245], s[10:11] offset:1024
	global_store_dwordx2 v1, v[246:247], s[10:11] offset:1536
	s_add_u32 s10, s10, 0x400000
	s_addc_u32 s11, s11, 0
	global_load_dwordx4 v[84:87], v0, s[8:9] nt
	global_load_dwordx4 v[88:91], v0, s[8:9] offset:1024 nt
	global_load_dwordx4 v[92:95], v0, s[8:9] offset:2048 nt
	global_load_dwordx4 v[96:99], v0, s[8:9] offset:3072 nt
	s_add_u32 s8, s8, 0x800000
	s_addc_u32 s9, s9, 0
	s_waitcnt vmcnt(32)
	v_pk_mul_f32 v[4:5], v[100:101], v[100:101]
	v_pk_fma_f32 v[4:5], v[102:103], v[102:103], v[4:5]
	v_pk_fma_f32 v[4:5], v[104:105], v[104:105], v[4:5]
	v_pk_fma_f32 v[4:5], v[106:107], v[106:107], v[4:5]
	v_pk_fma_f32 v[4:5], v[108:109], v[108:109], v[4:5]
	v_pk_fma_f32 v[4:5], v[110:111], v[110:111], v[4:5]
	v_pk_fma_f32 v[4:5], v[112:113], v[112:113], v[4:5]
	v_pk_fma_f32 v[4:5], v[114:115], v[114:115], v[4:5]
	v_add_f32_e32 v4, v4, v5
	s_nop 1
	v_add_f32_dpp v4, v4, v4 quad_perm:[1,0,3,2] row_mask:0xf bank_mask:0xf
	s_nop 1
	v_add_f32_dpp v4, v4, v4 quad_perm:[2,3,0,1] row_mask:0xf bank_mask:0xf
	s_nop 1
	v_add_f32_dpp v4, v4, v4 row_half_mirror row_mask:0xf bank_mask:0xf
	s_nop 1
	v_add_f32_dpp v4, v4, v4 row_mirror row_mask:0xf bank_mask:0xf
	s_nop 1
	v_add_f32_dpp v4, v4, v4 row_bcast:15 row_mask:0xa bank_mask:0xf
	s_nop 1
	v_add_f32_dpp v4, v4, v4 row_bcast:31 row_mask:0xc bank_mask:0xf
	s_nop 1
	v_readlane_b32 s20, v4, 63
	s_nop 1
	v_fma_f32 v6, s20, v16, v17
	v_rsq_f32_e32 v6, v6
	s_nop 0
	v_pk_mul_f32 v[100:101], v[100:101], v[6:7] op_sel_hi:[1,0]
	v_pk_mul_f32 v[102:103], v[102:103], v[6:7] op_sel_hi:[1,0]
	v_pk_mul_f32 v[104:105], v[104:105], v[6:7] op_sel_hi:[1,0]
	v_pk_mul_f32 v[106:107], v[106:107], v[6:7] op_sel_hi:[1,0]
	v_pk_mul_f32 v[108:109], v[108:109], v[6:7] op_sel_hi:[1,0]
	v_pk_mul_f32 v[110:111], v[110:111], v[6:7] op_sel_hi:[1,0]
	v_pk_mul_f32 v[112:113], v[112:113], v[6:7] op_sel_hi:[1,0]
	v_pk_mul_f32 v[114:115], v[114:115], v[6:7] op_sel_hi:[1,0]
	v_pk_mul_f32 v[100:101], v[100:101], v[20:21]
	v_pk_mul_f32 v[102:103], v[102:103], v[22:23]
	v_pk_mul_f32 v[104:105], v[104:105], v[24:25]
	v_pk_mul_f32 v[106:107], v[106:107], v[26:27]
	v_pk_mul_f32 v[108:109], v[108:109], v[28:29]
	v_pk_mul_f32 v[110:111], v[110:111], v[30:31]
	v_pk_mul_f32 v[112:113], v[112:113], v[32:33]
	v_pk_mul_f32 v[114:115], v[114:115], v[34:35]
	v_pk_fma_f32 v[100:101], v[100:101], v[52:53], v[36:37]
	v_pk_fma_f32 v[102:103], v[102:103], v[54:55], v[38:39]
	v_pk_fma_f32 v[104:105], v[104:105], v[56:57], v[40:41]
	v_pk_fma_f32 v[106:107], v[106:107], v[58:59], v[42:43]
	v_pk_fma_f32 v[108:109], v[108:109], v[60:61], v[44:45]
	v_pk_fma_f32 v[110:111], v[110:111], v[62:63], v[46:47]
	v_pk_fma_f32 v[112:113], v[112:113], v[64:65], v[48:49]
	v_pk_fma_f32 v[114:115], v[114:115], v[66:67], v[50:51]
	v_cvt_pk_bf16_f32 v232, v100, v101
	v_cvt_pk_bf16_f32 v233, v102, v103
	v_cvt_pk_bf16_f32 v234, v104, v105
	v_cvt_pk_bf16_f32 v235, v106, v107
	v_cvt_pk_bf16_f32 v236, v108, v109
	v_cvt_pk_bf16_f32 v237, v110, v111
	v_cvt_pk_bf16_f32 v238, v112, v113
	v_cvt_pk_bf16_f32 v239, v114, v115
	global_store_dwordx2 v1, v[232:233], s[10:11]
	global_store_dwordx2 v1, v[234:235], s[10:11] offset:512
	global_store_dwordx2 v1, v[236:237], s[10:11] offset:1024
	global_store_dwordx2 v1, v[238:239], s[10:11] offset:1536
	s_add_u32 s10, s10, 0x400000
	s_addc_u32 s11, s11, 0
	global_load_dwordx4 v[100:103], v0, s[8:9] nt
	global_load_dwordx4 v[104:107], v0, s[8:9] offset:1024 nt
	global_load_dwordx4 v[108:111], v0, s[8:9] offset:2048 nt
	global_load_dwordx4 v[112:115], v0, s[8:9] offset:3072 nt
	s_add_u32 s8, s8, 0x800000
	s_addc_u32 s9, s9, 0
	s_waitcnt vmcnt(32)
	v_pk_mul_f32 v[4:5], v[116:117], v[116:117]
	v_pk_fma_f32 v[4:5], v[118:119], v[118:119], v[4:5]
	v_pk_fma_f32 v[4:5], v[120:121], v[120:121], v[4:5]
	v_pk_fma_f32 v[4:5], v[122:123], v[122:123], v[4:5]
	v_pk_fma_f32 v[4:5], v[124:125], v[124:125], v[4:5]
	v_pk_fma_f32 v[4:5], v[126:127], v[126:127], v[4:5]
	v_pk_fma_f32 v[4:5], v[128:129], v[128:129], v[4:5]
	v_pk_fma_f32 v[4:5], v[130:131], v[130:131], v[4:5]
	v_add_f32_e32 v4, v4, v5
	s_nop 1
	v_add_f32_dpp v4, v4, v4 quad_perm:[1,0,3,2] row_mask:0xf bank_mask:0xf
	s_nop 1
	v_add_f32_dpp v4, v4, v4 quad_perm:[2,3,0,1] row_mask:0xf bank_mask:0xf
	s_nop 1
	v_add_f32_dpp v4, v4, v4 row_half_mirror row_mask:0xf bank_mask:0xf
	s_nop 1
	v_add_f32_dpp v4, v4, v4 row_mirror row_mask:0xf bank_mask:0xf
	s_nop 1
	v_add_f32_dpp v4, v4, v4 row_bcast:15 row_mask:0xa bank_mask:0xf
	s_nop 1
	v_add_f32_dpp v4, v4, v4 row_bcast:31 row_mask:0xc bank_mask:0xf
	s_nop 1
	v_readlane_b32 s20, v4, 63
	s_nop 1
	v_fma_f32 v6, s20, v16, v17
	v_rsq_f32_e32 v6, v6
	s_nop 0
	v_pk_mul_f32 v[116:117], v[116:117], v[6:7] op_sel_hi:[1,0]
	v_pk_mul_f32 v[118:119], v[118:119], v[6:7] op_sel_hi:[1,0]
	v_pk_mul_f32 v[120:121], v[120:121], v[6:7] op_sel_hi:[1,0]
	v_pk_mul_f32 v[122:123], v[122:123], v[6:7] op_sel_hi:[1,0]
	v_pk_mul_f32 v[124:125], v[124:125], v[6:7] op_sel_hi:[1,0]
	v_pk_mul_f32 v[126:127], v[126:127], v[6:7] op_sel_hi:[1,0]
	v_pk_mul_f32 v[128:129], v[128:129], v[6:7] op_sel_hi:[1,0]
	v_pk_mul_f32 v[130:131], v[130:131], v[6:7] op_sel_hi:[1,0]
	v_pk_mul_f32 v[116:117], v[116:117], v[20:21]
	v_pk_mul_f32 v[118:119], v[118:119], v[22:23]
	v_pk_mul_f32 v[120:121], v[120:121], v[24:25]
	v_pk_mul_f32 v[122:123], v[122:123], v[26:27]
	v_pk_mul_f32 v[124:125], v[124:125], v[28:29]
	v_pk_mul_f32 v[126:127], v[126:127], v[30:31]
	v_pk_mul_f32 v[128:129], v[128:129], v[32:33]
	v_pk_mul_f32 v[130:131], v[130:131], v[34:35]
	v_pk_fma_f32 v[116:117], v[116:117], v[52:53], v[36:37]
	v_pk_fma_f32 v[118:119], v[118:119], v[54:55], v[38:39]
	v_pk_fma_f32 v[120:121], v[120:121], v[56:57], v[40:41]
	v_pk_fma_f32 v[122:123], v[122:123], v[58:59], v[42:43]
	v_pk_fma_f32 v[124:125], v[124:125], v[60:61], v[44:45]
	v_pk_fma_f32 v[126:127], v[126:127], v[62:63], v[46:47]
	v_pk_fma_f32 v[128:129], v[128:129], v[64:65], v[48:49]
	v_pk_fma_f32 v[130:131], v[130:131], v[66:67], v[50:51]
	v_cvt_pk_bf16_f32 v240, v116, v117
	v_cvt_pk_bf16_f32 v241, v118, v119
	v_cvt_pk_bf16_f32 v242, v120, v121
	v_cvt_pk_bf16_f32 v243, v122, v123
	v_cvt_pk_bf16_f32 v244, v124, v125
	v_cvt_pk_bf16_f32 v245, v126, v127
	v_cvt_pk_bf16_f32 v246, v128, v129
	v_cvt_pk_bf16_f32 v247, v130, v131
	global_store_dwordx2 v1, v[240:241], s[10:11]
	global_store_dwordx2 v1, v[242:243], s[10:11] offset:512
	global_store_dwordx2 v1, v[244:245], s[10:11] offset:1024
	global_store_dwordx2 v1, v[246:247], s[10:11] offset:1536
	s_add_u32 s10, s10, 0x400000
	s_addc_u32 s11, s11, 0
	global_load_dwordx4 v[116:119], v0, s[8:9] nt
	global_load_dwordx4 v[120:123], v0, s[8:9] offset:1024 nt
	global_load_dwordx4 v[124:127], v0, s[8:9] offset:2048 nt
	global_load_dwordx4 v[128:131], v0, s[8:9] offset:3072 nt
	s_add_u32 s8, s8, 0x800000
	s_addc_u32 s9, s9, 0
	s_waitcnt vmcnt(24)
	v_pk_add_f32 v[164:165], v[164:165], v[18:19]
	v_pk_add_f32 v[166:167], v[166:167], v[18:19]
	v_pk_add_f32 v[168:169], v[168:169], v[18:19]
	v_pk_add_f32 v[170:171], v[170:171], v[18:19]
	v_pk_add_f32 v[172:173], v[172:173], v[18:19]
	v_pk_add_f32 v[174:175], v[174:175], v[18:19]
	v_pk_add_f32 v[176:177], v[176:177], v[18:19]
	v_pk_add_f32 v[178:179], v[178:179], v[18:19]
	s_add_u32 s14, s12, 0x18000
	s_addc_u32 s15, s13, 0
	s_add_u32 s16, s14, 0x1000
	s_addc_u32 s17, s15, 0
	global_load_dwordx4 v[36:39], v0, s[14:15]
	global_load_dwordx4 v[40:43], v0, s[14:15] offset:1024
	global_load_dwordx4 v[44:47], v0, s[14:15] offset:2048
	global_load_dwordx4 v[48:51], v0, s[14:15] offset:3072
	global_load_dwordx4 v[52:55], v0, s[16:17]
	global_load_dwordx4 v[56:59], v0, s[16:17] offset:1024
	global_load_dwordx4 v[60:63], v0, s[16:17] offset:2048
	global_load_dwordx4 v[64:67], v0, s[16:17] offset:3072
	v_pk_mul_f32 v[4:5], v[68:69], v[68:69]
	v_pk_fma_f32 v[4:5], v[70:71], v[70:71], v[4:5]
	v_pk_fma_f32 v[4:5], v[72:73], v[72:73], v[4:5]
	v_pk_fma_f32 v[4:5], v[74:75], v[74:75], v[4:5]
	v_pk_fma_f32 v[4:5], v[76:77], v[76:77], v[4:5]
	v_pk_fma_f32 v[4:5], v[78:79], v[78:79], v[4:5]
	v_pk_fma_f32 v[4:5], v[80:81], v[80:81], v[4:5]
	v_pk_fma_f32 v[4:5], v[82:83], v[82:83], v[4:5]
	v_add_f32_e32 v4, v4, v5
	s_nop 1
	v_add_f32_dpp v4, v4, v4 quad_perm:[1,0,3,2] row_mask:0xf bank_mask:0xf
	s_nop 1
	v_add_f32_dpp v4, v4, v4 quad_perm:[2,3,0,1] row_mask:0xf bank_mask:0xf
	s_nop 1
	v_add_f32_dpp v4, v4, v4 row_half_mirror row_mask:0xf bank_mask:0xf
	s_nop 1
	v_add_f32_dpp v4, v4, v4 row_mirror row_mask:0xf bank_mask:0xf
	s_nop 1
	v_add_f32_dpp v4, v4, v4 row_bcast:15 row_mask:0xa bank_mask:0xf
	s_nop 1
	v_add_f32_dpp v4, v4, v4 row_bcast:31 row_mask:0xc bank_mask:0xf
	s_nop 1
	v_readlane_b32 s20, v4, 63
	s_nop 1
	v_fma_f32 v6, s20, v16, v17
	v_rsq_f32_e32 v6, v6
	s_nop 0
	v_pk_mul_f32 v[68:69], v[68:69], v[6:7] op_sel_hi:[1,0]
	v_pk_mul_f32 v[70:71], v[70:71], v[6:7] op_sel_hi:[1,0]
	v_pk_mul_f32 v[72:73], v[72:73], v[6:7] op_sel_hi:[1,0]
	v_pk_mul_f32 v[74:75], v[74:75], v[6:7] op_sel_hi:[1,0]
	v_pk_mul_f32 v[76:77], v[76:77], v[6:7] op_sel_hi:[1,0]
	v_pk_mul_f32 v[78:79], v[78:79], v[6:7] op_sel_hi:[1,0]
	v_pk_mul_f32 v[80:81], v[80:81], v[6:7] op_sel_hi:[1,0]
	v_pk_mul_f32 v[82:83], v[82:83], v[6:7] op_sel_hi:[1,0]
	v_pk_mul_f32 v[68:69], v[68:69], v[20:21]
	v_pk_mul_f32 v[70:71], v[70:71], v[22:23]
	v_pk_mul_f32 v[72:73], v[72:73], v[24:25]
	v_pk_mul_f32 v[74:75], v[74:75], v[26:27]
	v_pk_mul_f32 v[76:77], v[76:77], v[28:29]
	v_pk_mul_f32 v[78:79], v[78:79], v[30:31]
	v_pk_mul_f32 v[80:81], v[80:81], v[32:33]
	v_pk_mul_f32 v[82:83], v[82:83], v[34:35]
	v_pk_fma_f32 v[68:69], v[68:69], v[164:165], v[148:149]
	v_pk_fma_f32 v[70:71], v[70:71], v[166:167], v[150:151]
	v_pk_fma_f32 v[72:73], v[72:73], v[168:169], v[152:153]
	v_pk_fma_f32 v[74:75], v[74:75], v[170:171], v[154:155]
	v_pk_fma_f32 v[76:77], v[76:77], v[172:173], v[156:157]
	v_pk_fma_f32 v[78:79], v[78:79], v[174:175], v[158:159]
	v_pk_fma_f32 v[80:81], v[80:81], v[176:177], v[160:161]
	v_pk_fma_f32 v[82:83], v[82:83], v[178:179], v[162:163]
	v_cvt_pk_bf16_f32 v232, v68, v69
	v_cvt_pk_bf16_f32 v233, v70, v71
	v_cvt_pk_bf16_f32 v234, v72, v73
	v_cvt_pk_bf16_f32 v235, v74, v75
	v_cvt_pk_bf16_f32 v236, v76, v77
	v_cvt_pk_bf16_f32 v237, v78, v79
	v_cvt_pk_bf16_f32 v238, v80, v81
	v_cvt_pk_bf16_f32 v239, v82, v83
	global_store_dwordx2 v1, v[232:233], s[10:11]
	global_store_dwordx2 v1, v[234:235], s[10:11] offset:512
	global_store_dwordx2 v1, v[236:237], s[10:11] offset:1024
	global_store_dwordx2 v1, v[238:239], s[10:11] offset:1536
	s_add_u32 s10, s10, 0x400000
	s_addc_u32 s11, s11, 0
	s_waitcnt vmcnt(28)
	v_pk_mul_f32 v[4:5], v[84:85], v[84:85]
	v_pk_fma_f32 v[4:5], v[86:87], v[86:87], v[4:5]
	v_pk_fma_f32 v[4:5], v[88:89], v[88:89], v[4:5]
	v_pk_fma_f32 v[4:5], v[90:91], v[90:91], v[4:5]
	v_pk_fma_f32 v[4:5], v[92:93], v[92:93], v[4:5]
	v_pk_fma_f32 v[4:5], v[94:95], v[94:95], v[4:5]
	v_pk_fma_f32 v[4:5], v[96:97], v[96:97], v[4:5]
	v_pk_fma_f32 v[4:5], v[98:99], v[98:99], v[4:5]
	v_add_f32_e32 v4, v4, v5
	s_nop 1
	v_add_f32_dpp v4, v4, v4 quad_perm:[1,0,3,2] row_mask:0xf bank_mask:0xf
	s_nop 1
	v_add_f32_dpp v4, v4, v4 quad_perm:[2,3,0,1] row_mask:0xf bank_mask:0xf
	s_nop 1
	v_add_f32_dpp v4, v4, v4 row_half_mirror row_mask:0xf bank_mask:0xf
	s_nop 1
	v_add_f32_dpp v4, v4, v4 row_mirror row_mask:0xf bank_mask:0xf
	s_nop 1
	v_add_f32_dpp v4, v4, v4 row_bcast:15 row_mask:0xa bank_mask:0xf
	s_nop 1
	v_add_f32_dpp v4, v4, v4 row_bcast:31 row_mask:0xc bank_mask:0xf
	s_nop 1
	v_readlane_b32 s20, v4, 63
	s_nop 1
	v_fma_f32 v6, s20, v16, v17
	v_rsq_f32_e32 v6, v6
	s_nop 0
	v_pk_mul_f32 v[84:85], v[84:85], v[6:7] op_sel_hi:[1,0]
	v_pk_mul_f32 v[86:87], v[86:87], v[6:7] op_sel_hi:[1,0]
	v_pk_mul_f32 v[88:89], v[88:89], v[6:7] op_sel_hi:[1,0]
	v_pk_mul_f32 v[90:91], v[90:91], v[6:7] op_sel_hi:[1,0]
	v_pk_mul_f32 v[92:93], v[92:93], v[6:7] op_sel_hi:[1,0]
	v_pk_mul_f32 v[94:95], v[94:95], v[6:7] op_sel_hi:[1,0]
	v_pk_mul_f32 v[96:97], v[96:97], v[6:7] op_sel_hi:[1,0]
	v_pk_mul_f32 v[98:99], v[98:99], v[6:7] op_sel_hi:[1,0]
	v_pk_mul_f32 v[84:85], v[84:85], v[20:21]
	v_pk_mul_f32 v[86:87], v[86:87], v[22:23]
	v_pk_mul_f32 v[88:89], v[88:89], v[24:25]
	v_pk_mul_f32 v[90:91], v[90:91], v[26:27]
	v_pk_mul_f32 v[92:93], v[92:93], v[28:29]
	v_pk_mul_f32 v[94:95], v[94:95], v[30:31]
	v_pk_mul_f32 v[96:97], v[96:97], v[32:33]
	v_pk_mul_f32 v[98:99], v[98:99], v[34:35]
	v_pk_fma_f32 v[84:85], v[84:85], v[164:165], v[148:149]
	v_pk_fma_f32 v[86:87], v[86:87], v[166:167], v[150:151]
	v_pk_fma_f32 v[88:89], v[88:89], v[168:169], v[152:153]
	v_pk_fma_f32 v[90:91], v[90:91], v[170:171], v[154:155]
	v_pk_fma_f32 v[92:93], v[92:93], v[172:173], v[156:157]
	v_pk_fma_f32 v[94:95], v[94:95], v[174:175], v[158:159]
	v_pk_fma_f32 v[96:97], v[96:97], v[176:177], v[160:161]
	v_pk_fma_f32 v[98:99], v[98:99], v[178:179], v[162:163]
	v_cvt_pk_bf16_f32 v240, v84, v85
	v_cvt_pk_bf16_f32 v241, v86, v87
	v_cvt_pk_bf16_f32 v242, v88, v89
	v_cvt_pk_bf16_f32 v243, v90, v91
	v_cvt_pk_bf16_f32 v244, v92, v93
	v_cvt_pk_bf16_f32 v245, v94, v95
	v_cvt_pk_bf16_f32 v246, v96, v97
	v_cvt_pk_bf16_f32 v247, v98, v99
	global_store_dwordx2 v1, v[240:241], s[10:11]
	global_store_dwordx2 v1, v[242:243], s[10:11] offset:512
	global_store_dwordx2 v1, v[244:245], s[10:11] offset:1024
	global_store_dwordx2 v1, v[246:247], s[10:11] offset:1536
	s_add_u32 s10, s10, 0x400000
	s_addc_u32 s11, s11, 0
	s_waitcnt vmcnt(24)
	v_pk_mul_f32 v[4:5], v[100:101], v[100:101]
	v_pk_fma_f32 v[4:5], v[102:103], v[102:103], v[4:5]
	v_pk_fma_f32 v[4:5], v[104:105], v[104:105], v[4:5]
	v_pk_fma_f32 v[4:5], v[106:107], v[106:107], v[4:5]
	v_pk_fma_f32 v[4:5], v[108:109], v[108:109], v[4:5]
	v_pk_fma_f32 v[4:5], v[110:111], v[110:111], v[4:5]
	v_pk_fma_f32 v[4:5], v[112:113], v[112:113], v[4:5]
	v_pk_fma_f32 v[4:5], v[114:115], v[114:115], v[4:5]
	v_add_f32_e32 v4, v4, v5
	s_nop 1
	v_add_f32_dpp v4, v4, v4 quad_perm:[1,0,3,2] row_mask:0xf bank_mask:0xf
	s_nop 1
	v_add_f32_dpp v4, v4, v4 quad_perm:[2,3,0,1] row_mask:0xf bank_mask:0xf
	s_nop 1
	v_add_f32_dpp v4, v4, v4 row_half_mirror row_mask:0xf bank_mask:0xf
	s_nop 1
	v_add_f32_dpp v4, v4, v4 row_mirror row_mask:0xf bank_mask:0xf
	s_nop 1
	v_add_f32_dpp v4, v4, v4 row_bcast:15 row_mask:0xa bank_mask:0xf
	s_nop 1
	v_add_f32_dpp v4, v4, v4 row_bcast:31 row_mask:0xc bank_mask:0xf
	s_nop 1
	v_readlane_b32 s20, v4, 63
	s_nop 1
	v_fma_f32 v6, s20, v16, v17
	v_rsq_f32_e32 v6, v6
	s_nop 0
	v_pk_mul_f32 v[100:101], v[100:101], v[6:7] op_sel_hi:[1,0]
	v_pk_mul_f32 v[102:103], v[102:103], v[6:7] op_sel_hi:[1,0]
	v_pk_mul_f32 v[104:105], v[104:105], v[6:7] op_sel_hi:[1,0]
	v_pk_mul_f32 v[106:107], v[106:107], v[6:7] op_sel_hi:[1,0]
	v_pk_mul_f32 v[108:109], v[108:109], v[6:7] op_sel_hi:[1,0]
	v_pk_mul_f32 v[110:111], v[110:111], v[6:7] op_sel_hi:[1,0]
	v_pk_mul_f32 v[112:113], v[112:113], v[6:7] op_sel_hi:[1,0]
	v_pk_mul_f32 v[114:115], v[114:115], v[6:7] op_sel_hi:[1,0]
	v_pk_mul_f32 v[100:101], v[100:101], v[20:21]
	v_pk_mul_f32 v[102:103], v[102:103], v[22:23]
	v_pk_mul_f32 v[104:105], v[104:105], v[24:25]
	v_pk_mul_f32 v[106:107], v[106:107], v[26:27]
	v_pk_mul_f32 v[108:109], v[108:109], v[28:29]
	v_pk_mul_f32 v[110:111], v[110:111], v[30:31]
	v_pk_mul_f32 v[112:113], v[112:113], v[32:33]
	v_pk_mul_f32 v[114:115], v[114:115], v[34:35]
	v_pk_fma_f32 v[100:101], v[100:101], v[164:165], v[148:149]
	v_pk_fma_f32 v[102:103], v[102:103], v[166:167], v[150:151]
	v_pk_fma_f32 v[104:105], v[104:105], v[168:169], v[152:153]
	v_pk_fma_f32 v[106:107], v[106:107], v[170:171], v[154:155]
	v_pk_fma_f32 v[108:109], v[108:109], v[172:173], v[156:157]
	v_pk_fma_f32 v[110:111], v[110:111], v[174:175], v[158:159]
	v_pk_fma_f32 v[112:113], v[112:113], v[176:177], v[160:161]
	v_pk_fma_f32 v[114:115], v[114:115], v[178:179], v[162:163]
	v_cvt_pk_bf16_f32 v232, v100, v101
	v_cvt_pk_bf16_f32 v233, v102, v103
	v_cvt_pk_bf16_f32 v234, v104, v105
	v_cvt_pk_bf16_f32 v235, v106, v107
	v_cvt_pk_bf16_f32 v236, v108, v109
	v_cvt_pk_bf16_f32 v237, v110, v111
	v_cvt_pk_bf16_f32 v238, v112, v113
	v_cvt_pk_bf16_f32 v239, v114, v115
	global_store_dwordx2 v1, v[232:233], s[10:11]
	global_store_dwordx2 v1, v[234:235], s[10:11] offset:512
	global_store_dwordx2 v1, v[236:237], s[10:11] offset:1024
	global_store_dwordx2 v1, v[238:239], s[10:11] offset:1536
	s_add_u32 s10, s10, 0x400000
	s_addc_u32 s11, s11, 0
	s_waitcnt vmcnt(20)
	v_pk_mul_f32 v[4:5], v[116:117], v[116:117]
	v_pk_fma_f32 v[4:5], v[118:119], v[118:119], v[4:5]
	v_pk_fma_f32 v[4:5], v[120:121], v[120:121], v[4:5]
	v_pk_fma_f32 v[4:5], v[122:123], v[122:123], v[4:5]
	v_pk_fma_f32 v[4:5], v[124:125], v[124:125], v[4:5]
	v_pk_fma_f32 v[4:5], v[126:127], v[126:127], v[4:5]
	v_pk_fma_f32 v[4:5], v[128:129], v[128:129], v[4:5]
	v_pk_fma_f32 v[4:5], v[130:131], v[130:131], v[4:5]
	v_add_f32_e32 v4, v4, v5
	s_nop 1
	v_add_f32_dpp v4, v4, v4 quad_perm:[1,0,3,2] row_mask:0xf bank_mask:0xf
	s_nop 1
	v_add_f32_dpp v4, v4, v4 quad_perm:[2,3,0,1] row_mask:0xf bank_mask:0xf
	s_nop 1
	v_add_f32_dpp v4, v4, v4 row_half_mirror row_mask:0xf bank_mask:0xf
	s_nop 1
	v_add_f32_dpp v4, v4, v4 row_mirror row_mask:0xf bank_mask:0xf
	s_nop 1
	v_add_f32_dpp v4, v4, v4 row_bcast:15 row_mask:0xa bank_mask:0xf
	s_nop 1
	v_add_f32_dpp v4, v4, v4 row_bcast:31 row_mask:0xc bank_mask:0xf
	s_nop 1
	v_readlane_b32 s20, v4, 63
	s_nop 1
	v_fma_f32 v6, s20, v16, v17
	v_rsq_f32_e32 v6, v6
	s_nop 0
	v_pk_mul_f32 v[116:117], v[116:117], v[6:7] op_sel_hi:[1,0]
	v_pk_mul_f32 v[118:119], v[118:119], v[6:7] op_sel_hi:[1,0]
	v_pk_mul_f32 v[120:121], v[120:121], v[6:7] op_sel_hi:[1,0]
	v_pk_mul_f32 v[122:123], v[122:123], v[6:7] op_sel_hi:[1,0]
	v_pk_mul_f32 v[124:125], v[124:125], v[6:7] op_sel_hi:[1,0]
	v_pk_mul_f32 v[126:127], v[126:127], v[6:7] op_sel_hi:[1,0]
	v_pk_mul_f32 v[128:129], v[128:129], v[6:7] op_sel_hi:[1,0]
	v_pk_mul_f32 v[130:131], v[130:131], v[6:7] op_sel_hi:[1,0]
	v_pk_mul_f32 v[116:117], v[116:117], v[20:21]
	v_pk_mul_f32 v[118:119], v[118:119], v[22:23]
	v_pk_mul_f32 v[120:121], v[120:121], v[24:25]
	v_pk_mul_f32 v[122:123], v[122:123], v[26:27]
	v_pk_mul_f32 v[124:125], v[124:125], v[28:29]
	v_pk_mul_f32 v[126:127], v[126:127], v[30:31]
	v_pk_mul_f32 v[128:129], v[128:129], v[32:33]
	v_pk_mul_f32 v[130:131], v[130:131], v[34:35]
	v_pk_fma_f32 v[116:117], v[116:117], v[164:165], v[148:149]
	v_pk_fma_f32 v[118:119], v[118:119], v[166:167], v[150:151]
	v_pk_fma_f32 v[120:121], v[120:121], v[168:169], v[152:153]
	v_pk_fma_f32 v[122:123], v[122:123], v[170:171], v[154:155]
	v_pk_fma_f32 v[124:125], v[124:125], v[172:173], v[156:157]
	v_pk_fma_f32 v[126:127], v[126:127], v[174:175], v[158:159]
	v_pk_fma_f32 v[128:129], v[128:129], v[176:177], v[160:161]
	v_pk_fma_f32 v[130:131], v[130:131], v[178:179], v[162:163]
	v_cvt_pk_bf16_f32 v240, v116, v117
	v_cvt_pk_bf16_f32 v241, v118, v119
	v_cvt_pk_bf16_f32 v242, v120, v121
	v_cvt_pk_bf16_f32 v243, v122, v123
	v_cvt_pk_bf16_f32 v244, v124, v125
	v_cvt_pk_bf16_f32 v245, v126, v127
	v_cvt_pk_bf16_f32 v246, v128, v129
	v_cvt_pk_bf16_f32 v247, v130, v131
	global_store_dwordx2 v1, v[240:241], s[10:11]
	global_store_dwordx2 v1, v[242:243], s[10:11] offset:512
	global_store_dwordx2 v1, v[244:245], s[10:11] offset:1024
	global_store_dwordx2 v1, v[246:247], s[10:11] offset:1536
	s_add_u32 s10, s10, 0x400000
	s_addc_u32 s11, s11, 0
	s_cmpk_lt_u32 s6, 0x400
	s_cbranch_scc0 .Lp1_done
	s_waitcnt vmcnt(16)
	v_pk_add_f32 v[52:53], v[52:53], v[18:19]
	v_pk_add_f32 v[54:55], v[54:55], v[18:19]
	v_pk_add_f32 v[56:57], v[56:57], v[18:19]
	v_pk_add_f32 v[58:59], v[58:59], v[18:19]
	v_pk_add_f32 v[60:61], v[60:61], v[18:19]
	v_pk_add_f32 v[62:63], v[62:63], v[18:19]
	v_pk_add_f32 v[64:65], v[64:65], v[18:19]
	v_pk_add_f32 v[66:67], v[66:67], v[18:19]
	s_lshl_b32 s10, s6, 11
	s_add_u32 s10, s10, 0x5e85000
	s_addc_u32 s11, 0, 0
	s_add_u32 s10, s74, s10
	s_addc_u32 s11, s75, s11
	v_pk_mul_f32 v[4:5], v[132:133], v[132:133]
	v_pk_fma_f32 v[4:5], v[134:135], v[134:135], v[4:5]
	v_pk_fma_f32 v[4:5], v[136:137], v[136:137], v[4:5]
	v_pk_fma_f32 v[4:5], v[138:139], v[138:139], v[4:5]
	v_pk_fma_f32 v[4:5], v[140:141], v[140:141], v[4:5]
	v_pk_fma_f32 v[4:5], v[142:143], v[142:143], v[4:5]
	v_pk_fma_f32 v[4:5], v[144:145], v[144:145], v[4:5]
	v_pk_fma_f32 v[4:5], v[146:147], v[146:147], v[4:5]
	v_add_f32_e32 v4, v4, v5
	s_nop 1
	v_add_f32_dpp v4, v4, v4 quad_perm:[1,0,3,2] row_mask:0xf bank_mask:0xf
	s_nop 1
	v_add_f32_dpp v4, v4, v4 quad_perm:[2,3,0,1] row_mask:0xf bank_mask:0xf
	s_nop 1
	v_add_f32_dpp v4, v4, v4 row_half_mirror row_mask:0xf bank_mask:0xf
	s_nop 1
	v_add_f32_dpp v4, v4, v4 row_mirror row_mask:0xf bank_mask:0xf
	s_nop 1
	v_add_f32_dpp v4, v4, v4 row_bcast:15 row_mask:0xa bank_mask:0xf
	s_nop 1
	v_add_f32_dpp v4, v4, v4 row_bcast:31 row_mask:0xc bank_mask:0xf
	s_nop 1
	v_readlane_b32 s20, v4, 63
	s_nop 1
	v_fma_f32 v6, s20, v16, v17
	v_rsq_f32_e32 v6, v6
	s_nop 0
	v_pk_mul_f32 v[132:133], v[132:133], v[6:7] op_sel_hi:[1,0]
	v_pk_mul_f32 v[134:135], v[134:135], v[6:7] op_sel_hi:[1,0]
	v_pk_mul_f32 v[136:137], v[136:137], v[6:7] op_sel_hi:[1,0]
	v_pk_mul_f32 v[138:139], v[138:139], v[6:7] op_sel_hi:[1,0]
	v_pk_mul_f32 v[140:141], v[140:141], v[6:7] op_sel_hi:[1,0]
	v_pk_mul_f32 v[142:143], v[142:143], v[6:7] op_sel_hi:[1,0]
	v_pk_mul_f32 v[144:145], v[144:145], v[6:7] op_sel_hi:[1,0]
	v_pk_mul_f32 v[146:147], v[146:147], v[6:7] op_sel_hi:[1,0]
	v_pk_mul_f32 v[132:133], v[132:133], v[20:21]
	v_pk_mul_f32 v[134:135], v[134:135], v[22:23]
	v_pk_mul_f32 v[136:137], v[136:137], v[24:25]
	v_pk_mul_f32 v[138:139], v[138:139], v[26:27]
	v_pk_mul_f32 v[140:141], v[140:141], v[28:29]
	v_pk_mul_f32 v[142:143], v[142:143], v[30:31]
	v_pk_mul_f32 v[144:145], v[144:145], v[32:33]
	v_pk_mul_f32 v[146:147], v[146:147], v[34:35]
	v_pk_fma_f32 v[132:133], v[132:133], v[52:53], v[36:37]
	v_pk_fma_f32 v[134:135], v[134:135], v[54:55], v[38:39]
	v_pk_fma_f32 v[136:137], v[136:137], v[56:57], v[40:41]
	v_pk_fma_f32 v[138:139], v[138:139], v[58:59], v[42:43]
	v_pk_fma_f32 v[140:141], v[140:141], v[60:61], v[44:45]
	v_pk_fma_f32 v[142:143], v[142:143], v[62:63], v[46:47]
	v_pk_fma_f32 v[144:145], v[144:145], v[64:65], v[48:49]
	v_pk_fma_f32 v[146:147], v[146:147], v[66:67], v[50:51]
	v_cvt_pk_bf16_f32 v232, v132, v133
	v_cvt_pk_bf16_f32 v233, v134, v135
	v_cvt_pk_bf16_f32 v234, v136, v137
	v_cvt_pk_bf16_f32 v235, v138, v139
	v_cvt_pk_bf16_f32 v236, v140, v141
	v_cvt_pk_bf16_f32 v237, v142, v143
	v_cvt_pk_bf16_f32 v238, v144, v145
	v_cvt_pk_bf16_f32 v239, v146, v147
	global_store_dwordx2 v1, v[232:233], s[10:11]
	global_store_dwordx2 v1, v[234:235], s[10:11] offset:512
	global_store_dwordx2 v1, v[236:237], s[10:11] offset:1024
	global_store_dwordx2 v1, v[238:239], s[10:11] offset:1536
